# hoisted serialized load-then-wait chains: gatenorm gate loads (16 per chunk), gemm3 epilogue row-sum loads, gemm2 epilogue residual-row loads are issued up front instead of one per 4-row group
# speedup vs baseline: 1.1675x; 1.0325x over previous
; __device__ __forceinline__ u16 f2bf(float f) { return (u16)(pack2(f, 0.f) & 0xffffu); }
; __device__ __forceinline__ float bf2f(u16 h) { return __uint_as_float(((unsigned)h) << 16); }
; __device__ __forceinline__ float silu(float y) { return y / (1.f + __expf(-y)); }
; __device__ void ph_gatenorm(const P& p) {
;     ...
;     const int n = chunk & 127, h = (chunk >> 7) & 7, b = chunk >> 10;
;     f32x4 o[4];
;     float ss[4] = {0.f, 0.f, 0.f, 0.f};
; #pragma unroll
;     for (int nt = 0; nt < 4; ++nt) {
;       o[nt] = *(const f32x4*)(Ubuf + (size_t)chunk * 4096 + ((w * 4 + nt) * 64 + lane) * 4);
; #pragma unroll
;       for (int r = 0; r < 4; ++r) ss[r] += o[nt][r] * o[nt][r];
;     }
; #pragma unroll
;     for (int r = 0; r < 4; ++r) {
;       float s = ss[r];
;       s += __shfl_xor(s, 1); s += __shfl_xor(s, 2); s += __shfl_xor(s, 4); s += __shfl_xor(s, 8);
;       ss[r] = rsqrtf(s * (1.f / 64.f) + EPS);
;     }
; #pragma unroll
;     for (int nt = 0; nt < 4; ++nt) {
;       const float gn = p.dn_norm[nt * 16 + fr];
; #pragma unroll
;       for (int r = 0; r < 4; ++r) {
;         size_t tok = (size_t)b * 8192 + n * 64 + w * 16 + fq * 4 + r;
;         float z = bf2f(p_proj[tok * INW + 2304 + h * 64 + nt * 16 + fr]);
;         p_mix[tok * DM + 512 + h * 64 + nt * 16 + fr] = f2bf(o[nt][r] * ss[r] * gn * silu(z));
;       }
;     }
.LBB0_542:
	s_ashr_i32 s15, s14, 31
	s_lshl_b64 s[4:5], s[14:15], 14
	v_lshl_add_u64 v[28:29], v[22:23], 0, s[4:5]
	global_load_dwordx4 v[12:15], v[28:29], off
	global_load_dwordx4 v[8:11], v[28:29], off offset:1024
	global_load_dwordx4 v[4:7], v[28:29], off offset:2048
	global_load_dwordx4 v[0:3], v[28:29], off offset:3072
	s_ashr_i32 s0, s14, 10
	s_ashr_i32 s1, s0, 31
	s_and_b32 s22, s7, 0x1fc0
	s_lshl_b64 s[0:1], s[0:1], 13
	s_and_b32 s2, s14, 0x380
	s_or_b32 s0, s0, s22
	v_lshl_add_u64 v[26:27], v[18:19], 0, s[2:3]
	v_lshl_add_u64 v[30:31], s[0:1], 0, v[16:17]
	v_mad_u64_u32 v[26:27], s[0:1], v30, s18, v[26:27]
	v_lshlrev_b64 v[36:37], 11, v[30:31]
	v_mov_b32_e32 v30, v27
	v_mad_u64_u32 v[48:49], s[0:1], v31, s18, v[30:31]
	v_mov_b32_e32 v27, v48
	global_load_ushort v70, v[26:27], off
	v_lshl_add_u64 v[100:101], v[26:27], 0, s[8:9]
	v_lshl_add_u64 v[102:103], v[26:27], 0, s[10:11]
	v_lshl_add_u64 v[104:105], v[26:27], 0, s[12:13]
	global_load_ushort v111, v[100:101], off
	global_load_ushort v112, v[102:103], off
	global_load_ushort v113, v[104:105], off
	global_load_ushort v114, v[26:27], off offset:32
	global_load_ushort v115, v[100:101], off offset:32
	global_load_ushort v116, v[102:103], off offset:32
	global_load_ushort v117, v[104:105], off offset:32
	global_load_ushort v118, v[26:27], off offset:64
	global_load_ushort v119, v[100:101], off offset:64
	global_load_ushort v120, v[102:103], off offset:64
	global_load_ushort v121, v[104:105], off offset:64
	global_load_ushort v122, v[26:27], off offset:96
	global_load_ushort v123, v[100:101], off offset:96
	global_load_ushort v124, v[102:103], off offset:96
	global_load_ushort v125, v[104:105], off offset:96
	v_lshl_add_u64 v[34:35], v[20:21], 0, s[2:3]
	v_or_b32_e32 v46, 0x1000, v36
	v_mov_b32_e32 v47, v37
	v_add_co_u32_e32 v50, vcc, s19, v26
	v_add_co_u32_e64 v52, s[0:1], s20, v26
	v_lshl_add_u64 v[30:31], v[34:35], 0, v[46:47]
	v_add_co_u32_e64 v46, s[4:5], s21, v26
	v_addc_co_u32_e32 v51, vcc, 0, v48, vcc
	v_addc_co_u32_e64 v53, vcc, 0, v48, s[0:1]
	v_addc_co_u32_e64 v47, vcc, 0, v48, s[4:5]
	v_lshl_add_u64 v[28:29], v[34:35], 0, v[36:37]
	v_or_b32_e32 v32, 0x800, v36
	v_mov_b32_e32 v33, v37
	v_lshl_add_u64 v[32:33], v[34:35], 0, v[32:33]
	v_or_b32_e32 v36, 0x1800, v36
	s_add_i32 s14, s14, s24
	s_waitcnt vmcnt(0)
	v_mov_b32_e32 v48, v12
	v_mov_b32_e32 v49, v8
	v_mov_b32_e32 v54, v13
	v_mov_b32_e32 v55, v9
	v_mov_b32_e32 v60, v4
	v_mov_b32_e32 v61, v0
	v_mov_b32_e32 v62, v5
	v_mov_b32_e32 v63, v1
	v_pk_mul_f32 v[48:49], v[48:49], v[48:49]
	v_pk_mul_f32 v[54:55], v[54:55], v[54:55]
	v_mov_b32_e32 v56, v14
	v_mov_b32_e32 v57, v10
	v_mov_b32_e32 v58, v15
	v_mov_b32_e32 v59, v11
	v_pk_mul_f32 v[60:61], v[60:61], v[60:61]
	v_pk_mul_f32 v[62:63], v[62:63], v[62:63]
	v_mov_b32_e32 v68, v54
	v_mov_b32_e32 v69, v48
	v_mov_b32_e32 v48, v55
	v_mov_b32_e32 v64, v6
	v_mov_b32_e32 v65, v2
	v_mov_b32_e32 v66, v7
	v_mov_b32_e32 v67, v3
	v_pk_mul_f32 v[56:57], v[56:57], v[56:57]
	v_pk_mul_f32 v[58:59], v[58:59], v[58:59]
	v_mov_b32_e32 v54, v62
	v_mov_b32_e32 v55, v60
	v_pk_add_f32 v[48:49], v[68:69], v[48:49]
	v_pk_mul_f32 v[64:65], v[64:65], v[64:65]
	v_pk_mul_f32 v[66:67], v[66:67], v[66:67]
	v_mov_b32_e32 v60, v63
	v_mov_b32_e32 v62, v58
	v_mov_b32_e32 v63, v56
	v_mov_b32_e32 v56, v59
	v_pk_add_f32 v[48:49], v[48:49], v[54:55]
	v_mov_b32_e32 v58, v66
	v_mov_b32_e32 v59, v64
	v_pk_add_f32 v[56:57], v[62:63], v[56:57]
	v_pk_add_f32 v[48:49], v[48:49], v[60:61]
	v_pk_add_f32 v[54:55], v[56:57], v[58:59]
	ds_bpermute_b32 v57, v42, v49
	ds_bpermute_b32 v56, v42, v48
	v_lshlrev_b32_e32 v58, 16, v70
	v_mul_f32_e32 v60, 0xbfb8aa3b, v58
	v_exp_f32_e32 v60, v60
	v_mov_b32_e32 v64, v67
	s_waitcnt lgkmcnt(0)
	v_pk_add_f32 v[48:49], v[48:49], v[56:57]
	ds_bpermute_b32 v57, v43, v49
	ds_bpermute_b32 v56, v43, v48
	v_add_f32_e32 v60, 1.0, v60
	v_div_scale_f32 v61, s[0:1], v60, v60, v58
	v_rcp_f32_e32 v63, v61
	s_waitcnt lgkmcnt(0)
	v_pk_add_f32 v[48:49], v[48:49], v[56:57]
	ds_bpermute_b32 v57, v44, v49
	ds_bpermute_b32 v56, v44, v48
	v_pk_add_f32 v[54:55], v[54:55], v[64:65]
	v_fma_f32 v64, -v61, v63, 1.0
	v_div_scale_f32 v62, vcc, v58, v60, v58
	s_waitcnt lgkmcnt(0)
	v_pk_add_f32 v[48:49], v[48:49], v[56:57]
	ds_bpermute_b32 v57, v45, v49
	ds_bpermute_b32 v56, v45, v48
	v_fmac_f32_e32 v63, v64, v63
	v_mul_f32_e32 v64, v62, v63
	v_fma_f32 v65, -v61, v64, v62
	v_fmac_f32_e32 v64, v65, v63
	s_waitcnt lgkmcnt(0)
	v_pk_add_f32 v[48:49], v[48:49], v[56:57]
	v_fma_f32 v61, -v61, v64, v62
	v_pk_fma_f32 v[48:49], v[48:49], s[6:7], v[24:25] op_sel_hi:[1,0,0]
	v_div_fmas_f32 v61, v61, v63, v64
	v_mul_f32_e32 v56, 0x4b800000, v49
	v_cmp_gt_f32_e32 vcc, s17, v49
	v_div_fixup_f32 v58, v61, v60, v58
	ds_bpermute_b32 v59, v42, v55
	v_cndmask_b32_e32 v49, v49, v56, vcc
	v_rsq_f32_e32 v49, v49
	s_nop 0
	v_mul_f32_e32 v56, 0x45800000, v49
	v_cndmask_b32_e32 v56, v49, v56, vcc
	v_mul_f32_e32 v12, v12, v56
	v_mul_f32_e32 v12, v38, v12
	v_mul_f32_e32 v12, v12, v58
	v_cvt_pk_bf16_f32 v12, v12, s0
	global_store_short v[28:29], v12, off
	v_mov_b32_e32 v12, v111
	ds_bpermute_b32 v58, v42, v54
	v_cmp_gt_f32_e32 vcc, s17, v48
	v_mul_f32_e32 v8, v8, v56
	v_mul_f32_e32 v8, v39, v8
	v_mul_f32_e32 v4, v4, v56
	s_waitcnt lgkmcnt(0)
	v_pk_add_f32 v[50:51], v[54:55], v[58:59]
	ds_bpermute_b32 v55, v43, v51
	ds_bpermute_b32 v54, v43, v50
	v_mul_f32_e32 v4, v40, v4
	v_mul_f32_e32 v0, v0, v56
	v_mul_f32_e32 v0, v41, v0
	s_waitcnt lgkmcnt(0)
; __device__ __forceinline__ u16 f2bf(float f) { return (u16)(pack2(f, 0.f) & 0xffffu); }
; __device__ __forceinline__ float bf2f(u16 h) { return __uint_as_float(((unsigned)h) << 16); }
; __device__ __forceinline__ float silu(float y) { return y / (1.f + __expf(-y)); }
; __device__ void ph_gatenorm(const P& p) {
;     ...
; #pragma unroll
;     for (int r = 0; r < 4; ++r) {
;       float s = ss[r];
;       s += __shfl_xor(s, 1); s += __shfl_xor(s, 2); s += __shfl_xor(s, 4); s += __shfl_xor(s, 8);
;       ss[r] = rsqrtf(s * (1.f / 64.f) + EPS);
;     }
; #pragma unroll
;     for (int nt = 0; nt < 4; ++nt) {
;       const float gn = p.dn_norm[nt * 16 + fr];
; #pragma unroll
;       for (int r = 0; r < 4; ++r) {
;         size_t tok = (size_t)b * 8192 + n * 64 + w * 16 + fq * 4 + r;
;         float z = bf2f(p_proj[tok * INW + 2304 + h * 64 + nt * 16 + fr]);
;         p_mix[tok * DM + 512 + h * 64 + nt * 16 + fr] = f2bf(o[nt][r] * ss[r] * gn * silu(z));
;       }
;     }
	v_pk_add_f32 v[50:51], v[50:51], v[54:55]
	v_mul_f32_e32 v54, 0x4b800000, v48
	v_cndmask_b32_e32 v48, v48, v54, vcc
	v_rsq_f32_e32 v48, v48
	ds_bpermute_b32 v49, v44, v51
	v_mul_f32_e32 v54, 0x45800000, v48
	v_cndmask_b32_e32 v54, v48, v54, vcc
	v_mul_f32_e32 v13, v13, v54
	v_mul_f32_e32 v13, v38, v13
	v_mul_f32_e32 v9, v9, v54
	v_mul_f32_e32 v9, v39, v9
	v_mul_f32_e32 v5, v5, v54
	v_mul_f32_e32 v5, v40, v5
	v_mul_f32_e32 v1, v1, v54
	v_mul_f32_e32 v1, v41, v1
	s_nop 0
	v_lshlrev_b32_e32 v12, 16, v12
	v_mul_f32_e32 v48, 0xbfb8aa3b, v12
	v_exp_f32_e32 v48, v48
	s_nop 0
	v_add_f32_e32 v48, 1.0, v48
	v_div_scale_f32 v55, s[0:1], v48, v48, v12
	v_rcp_f32_e32 v58, v55
	v_div_scale_f32 v57, vcc, v12, v48, v12
	v_fma_f32 v59, -v55, v58, 1.0
	v_fmac_f32_e32 v58, v59, v58
	v_mul_f32_e32 v59, v57, v58
	v_fma_f32 v60, -v55, v59, v57
	v_fmac_f32_e32 v59, v60, v58
	v_fma_f32 v55, -v55, v59, v57
	v_div_fmas_f32 v55, v55, v58, v59
	v_div_fixup_f32 v12, v55, v48, v12
	v_mul_f32_e32 v12, v13, v12
	v_cvt_pk_bf16_f32 v12, v12, s0
	global_store_short v[32:33], v12, off
	v_mov_b32_e32 v52, v112
	ds_bpermute_b32 v48, v44, v50
	s_waitcnt lgkmcnt(0)
	v_pk_add_f32 v[12:13], v[50:51], v[48:49]
	ds_bpermute_b32 v49, v45, v13
	ds_bpermute_b32 v48, v45, v12
	s_waitcnt lgkmcnt(0)
	v_pk_add_f32 v[12:13], v[12:13], v[48:49]
	s_nop 0
	v_pk_fma_f32 v[48:49], v[12:13], s[6:7], v[24:25] op_sel_hi:[1,0,0]
	s_add_i32 s7, s7, s16
	v_mul_f32_e32 v12, 0x4b800000, v49
	v_cmp_gt_f32_e32 vcc, s17, v49
	s_cmpk_lt_i32 s14, 0x1000
	s_nop 0
	v_cndmask_b32_e32 v12, v49, v12, vcc
	v_rsq_f32_e32 v12, v12
	s_nop 0
	v_mul_f32_e32 v13, 0x45800000, v12
	v_cndmask_b32_e32 v49, v12, v13, vcc
	v_mul_f32_e32 v12, v14, v49
	v_mul_f32_e32 v12, v38, v12
	v_mul_f32_e32 v10, v10, v49
	v_mul_f32_e32 v10, v39, v10
	s_nop 0
	v_lshlrev_b32_e32 v13, 16, v52
	v_mul_f32_e32 v14, 0xbfb8aa3b, v13
	v_exp_f32_e32 v14, v14
	s_nop 0
	v_add_f32_e32 v14, 1.0, v14
	v_div_scale_f32 v50, s[0:1], v14, v14, v13
	v_rcp_f32_e32 v52, v50
	v_div_scale_f32 v51, vcc, v13, v14, v13
	v_fma_f32 v53, -v50, v52, 1.0
	v_fmac_f32_e32 v52, v53, v52
	v_mul_f32_e32 v53, v51, v52
	v_fma_f32 v55, -v50, v53, v51
	v_fmac_f32_e32 v53, v55, v52
	v_fma_f32 v50, -v50, v53, v51
	v_div_fmas_f32 v50, v50, v52, v53
	v_div_fixup_f32 v13, v50, v14, v13
	v_mul_f32_e32 v12, v12, v13
	v_cvt_pk_bf16_f32 v12, v12, s0
	global_store_short v[30:31], v12, off
	v_mov_b32_e32 v14, v113
	v_lshl_add_u64 v[12:13], v[34:35], 0, v[36:37]
	v_mul_f32_e32 v34, 0x4b800000, v48
	v_cmp_gt_f32_e32 vcc, s17, v48
	s_nop 0
	v_lshlrev_b32_e32 v14, 16, v14
	v_cndmask_b32_e32 v34, v48, v34, vcc
	v_rsq_f32_e32 v34, v34
	s_nop 0
	v_mul_f32_e32 v35, 0x45800000, v34
	v_cndmask_b32_e32 v36, v34, v35, vcc
	v_mul_f32_e32 v34, 0xbfb8aa3b, v14
	v_exp_f32_e32 v34, v34
	v_mul_f32_e32 v15, v15, v36
	v_mul_f32_e32 v15, v38, v15
	v_mul_f32_e32 v11, v11, v36
	v_add_f32_e32 v34, 1.0, v34
	v_div_scale_f32 v35, s[0:1], v34, v34, v14
	v_rcp_f32_e32 v46, v35
	v_div_scale_f32 v37, vcc, v14, v34, v14
	v_mul_f32_e32 v11, v39, v11
	v_fma_f32 v47, -v35, v46, 1.0
	v_fmac_f32_e32 v46, v47, v46
	v_mul_f32_e32 v47, v37, v46
	v_fma_f32 v48, -v35, v47, v37
	v_fmac_f32_e32 v47, v48, v46
	v_fma_f32 v35, -v35, v47, v37
	v_div_fmas_f32 v35, v35, v46, v47
	v_div_fixup_f32 v14, v35, v34, v14
	v_mul_f32_e32 v14, v15, v14
	v_cvt_pk_bf16_f32 v14, v14, s0
	global_store_short v[12:13], v14, off
	v_mov_b32_e32 v34, v114
	v_lshl_add_u64 v[14:15], v[26:27], 0, s[8:9]
	s_nop 0
	v_lshlrev_b32_e32 v34, 16, v34
	v_mul_f32_e32 v35, 0xbfb8aa3b, v34
	v_exp_f32_e32 v35, v35
	s_nop 0
	v_add_f32_e32 v35, 1.0, v35
	v_div_scale_f32 v37, s[0:1], v35, v35, v34
	v_rcp_f32_e32 v47, v37
	v_div_scale_f32 v46, vcc, v34, v35, v34
	v_fma_f32 v48, -v37, v47, 1.0
	v_fmac_f32_e32 v47, v48, v47
	v_mul_f32_e32 v48, v46, v47
	v_fma_f32 v50, -v37, v48, v46
	v_fmac_f32_e32 v48, v50, v47
	v_fma_f32 v37, -v37, v48, v46
	v_div_fmas_f32 v37, v37, v47, v48
	v_div_fixup_f32 v34, v37, v35, v34
	v_mul_f32_e32 v8, v8, v34
	v_cvt_pk_bf16_f32 v8, v8, s0
	global_store_short v[28:29], v8, off offset:32
	v_mov_b32_e32 v8, v115
	v_lshl_add_u64 v[34:35], v[26:27], 0, s[10:11]
	s_nop 0
	v_lshlrev_b32_e32 v8, 16, v8
	v_mul_f32_e32 v37, 0xbfb8aa3b, v8
	v_exp_f32_e32 v37, v37
	s_nop 0
	v_add_f32_e32 v37, 1.0, v37
	v_div_scale_f32 v46, s[0:1], v37, v37, v8
	v_rcp_f32_e32 v48, v46
	v_div_scale_f32 v47, vcc, v8, v37, v8
	v_fma_f32 v50, -v46, v48, 1.0
	v_fmac_f32_e32 v48, v50, v48
	v_mul_f32_e32 v50, v47, v48
	v_fma_f32 v51, -v46, v50, v47
	v_fmac_f32_e32 v50, v51, v48
	v_fma_f32 v46, -v46, v50, v47
	v_div_fmas_f32 v46, v46, v48, v50
	v_div_fixup_f32 v8, v46, v37, v8
	v_mul_f32_e32 v8, v9, v8
	v_cvt_pk_bf16_f32 v8, v8, s0
	global_store_short v[32:33], v8, off offset:32
	v_mov_b32_e32 v37, v116
	v_lshl_add_u64 v[8:9], v[26:27], 0, s[12:13]
	s_nop 0
	v_lshlrev_b32_e32 v37, 16, v37
	v_mul_f32_e32 v46, 0xbfb8aa3b, v37
	v_exp_f32_e32 v46, v46
	s_nop 0
	v_add_f32_e32 v46, 1.0, v46
	v_div_scale_f32 v47, s[0:1], v46, v46, v37
	v_rcp_f32_e32 v50, v47
	v_div_scale_f32 v48, vcc, v37, v46, v37
	v_fma_f32 v51, -v47, v50, 1.0
	v_fmac_f32_e32 v50, v51, v50
	v_mul_f32_e32 v51, v48, v50
	v_fma_f32 v52, -v47, v51, v48
	v_fmac_f32_e32 v51, v52, v50
	v_fma_f32 v47, -v47, v51, v48
	v_div_fmas_f32 v47, v47, v50, v51
	v_div_fixup_f32 v37, v47, v46, v37
	v_mul_f32_e32 v10, v10, v37
	v_cvt_pk_bf16_f32 v10, v10, s0
	global_store_short v[30:31], v10, off offset:32
	v_mov_b32_e32 v10, v117
	s_nop 0
	v_lshlrev_b32_e32 v10, 16, v10
	v_mul_f32_e32 v37, 0xbfb8aa3b, v10
	v_exp_f32_e32 v37, v37
	s_nop 0
	v_add_f32_e32 v37, 1.0, v37
; __device__ __forceinline__ u16 f2bf(float f) { return (u16)(pack2(f, 0.f) & 0xffffu); }
; __device__ __forceinline__ float bf2f(u16 h) { return __uint_as_float(((unsigned)h) << 16); }
; __device__ __forceinline__ float silu(float y) { return y / (1.f + __expf(-y)); }
; __device__ void ph_gatenorm(const P& p) {
;     ...
;     for (int nt = 0; nt < 4; ++nt) {
;       const float gn = p.dn_norm[nt * 16 + fr];
; #pragma unroll
;       for (int r = 0; r < 4; ++r) {
;         size_t tok = (size_t)b * 8192 + n * 64 + w * 16 + fq * 4 + r;
;         float z = bf2f(p_proj[tok * INW + 2304 + h * 64 + nt * 16 + fr]);
;         p_mix[tok * DM + 512 + h * 64 + nt * 16 + fr] = f2bf(o[nt][r] * ss[r] * gn * silu(z));
;       }
;     }
	v_div_scale_f32 v46, s[0:1], v37, v37, v10
	v_rcp_f32_e32 v48, v46
	v_div_scale_f32 v47, vcc, v10, v37, v10
	v_fma_f32 v50, -v46, v48, 1.0
	v_fmac_f32_e32 v48, v50, v48
	v_mul_f32_e32 v50, v47, v48
	v_fma_f32 v51, -v46, v50, v47
	v_fmac_f32_e32 v50, v51, v48
	v_fma_f32 v46, -v46, v50, v47
	v_div_fmas_f32 v46, v46, v48, v50
	v_div_fixup_f32 v10, v46, v37, v10
	v_mul_f32_e32 v10, v11, v10
	v_cvt_pk_bf16_f32 v10, v10, s0
	global_store_short v[12:13], v10, off offset:32
	v_mov_b32_e32 v10, v118
	s_nop 0
	v_lshlrev_b32_e32 v10, 16, v10
	v_mul_f32_e32 v11, 0xbfb8aa3b, v10
	v_exp_f32_e32 v11, v11
	s_nop 0
	v_add_f32_e32 v11, 1.0, v11
	v_div_scale_f32 v37, s[0:1], v11, v11, v10
	v_rcp_f32_e32 v47, v37
	v_div_scale_f32 v46, vcc, v10, v11, v10
	v_fma_f32 v48, -v37, v47, 1.0
	v_fmac_f32_e32 v47, v48, v47
	v_mul_f32_e32 v48, v46, v47
	v_fma_f32 v50, -v37, v48, v46
	v_fmac_f32_e32 v48, v50, v47
	v_fma_f32 v37, -v37, v48, v46
	v_div_fmas_f32 v37, v37, v47, v48
	v_div_fixup_f32 v10, v37, v11, v10
	v_mul_f32_e32 v4, v4, v10
	v_cvt_pk_bf16_f32 v4, v4, s0
	global_store_short v[28:29], v4, off offset:64
	v_mov_b32_e32 v4, v119
	s_nop 0
	v_lshlrev_b32_e32 v4, 16, v4
	v_mul_f32_e32 v10, 0xbfb8aa3b, v4
	v_exp_f32_e32 v10, v10
	s_nop 0
	v_add_f32_e32 v10, 1.0, v10
	v_div_scale_f32 v11, s[0:1], v10, v10, v4
	v_rcp_f32_e32 v46, v11
	v_div_scale_f32 v37, vcc, v4, v10, v4
	v_fma_f32 v47, -v11, v46, 1.0
	v_fmac_f32_e32 v46, v47, v46
	v_mul_f32_e32 v47, v37, v46
	v_fma_f32 v48, -v11, v47, v37
	v_fmac_f32_e32 v47, v48, v46
	v_fma_f32 v11, -v11, v47, v37
	v_div_fmas_f32 v11, v11, v46, v47
	v_div_fixup_f32 v4, v11, v10, v4
	v_mul_f32_e32 v4, v5, v4
	v_cvt_pk_bf16_f32 v4, v4, s0
	global_store_short v[32:33], v4, off offset:64
	v_mov_b32_e32 v4, v120
	v_mul_f32_e32 v5, v6, v49
	v_mul_f32_e32 v5, v40, v5
	s_nop 0
	v_lshlrev_b32_e32 v4, 16, v4
	v_mul_f32_e32 v6, 0xbfb8aa3b, v4
	v_exp_f32_e32 v6, v6
	s_nop 0
	v_add_f32_e32 v6, 1.0, v6
	v_div_scale_f32 v10, s[0:1], v6, v6, v4
	v_rcp_f32_e32 v37, v10
	v_div_scale_f32 v11, vcc, v4, v6, v4
	v_fma_f32 v46, -v10, v37, 1.0
	v_fmac_f32_e32 v37, v46, v37
	v_mul_f32_e32 v46, v11, v37
	v_fma_f32 v47, -v10, v46, v11
	v_fmac_f32_e32 v46, v47, v37
	v_fma_f32 v10, -v10, v46, v11
	v_div_fmas_f32 v10, v10, v37, v46
	v_div_fixup_f32 v4, v10, v6, v4
	v_mul_f32_e32 v4, v5, v4
	v_cvt_pk_bf16_f32 v4, v4, s0
	global_store_short v[30:31], v4, off offset:64
	v_mov_b32_e32 v4, v121
	v_mul_f32_e32 v5, v7, v36
	v_mul_f32_e32 v5, v40, v5
	s_nop 0
	v_lshlrev_b32_e32 v4, 16, v4
	v_mul_f32_e32 v6, 0xbfb8aa3b, v4
	v_exp_f32_e32 v6, v6
	s_nop 0
	v_add_f32_e32 v6, 1.0, v6
	v_div_scale_f32 v7, s[0:1], v6, v6, v4
	v_rcp_f32_e32 v11, v7
	v_div_scale_f32 v10, vcc, v4, v6, v4
	v_fma_f32 v37, -v7, v11, 1.0
	v_fmac_f32_e32 v11, v37, v11
	v_mul_f32_e32 v37, v10, v11
	v_fma_f32 v46, -v7, v37, v10
	v_fmac_f32_e32 v37, v46, v11
	v_fma_f32 v7, -v7, v37, v10
	v_div_fmas_f32 v7, v7, v11, v37
	v_div_fixup_f32 v4, v7, v6, v4
	v_mul_f32_e32 v4, v5, v4
	v_cvt_pk_bf16_f32 v4, v4, s0
	global_store_short v[12:13], v4, off offset:64
	v_mov_b32_e32 v4, v122
	s_nop 0
	v_lshlrev_b32_e32 v4, 16, v4
	v_mul_f32_e32 v5, 0xbfb8aa3b, v4
	v_exp_f32_e32 v5, v5
	s_nop 0
	v_add_f32_e32 v5, 1.0, v5
	v_div_scale_f32 v6, s[0:1], v5, v5, v4
	v_rcp_f32_e32 v10, v6
	v_div_scale_f32 v7, vcc, v4, v5, v4
	v_fma_f32 v11, -v6, v10, 1.0
	v_fmac_f32_e32 v10, v11, v10
	v_mul_f32_e32 v11, v7, v10
	v_fma_f32 v26, -v6, v11, v7
	v_fmac_f32_e32 v11, v26, v10
	v_fma_f32 v6, -v6, v11, v7
	v_div_fmas_f32 v6, v6, v10, v11
	v_div_fixup_f32 v4, v6, v5, v4
	v_mul_f32_e32 v0, v0, v4
	v_cvt_pk_bf16_f32 v0, v0, s0
	global_store_short v[28:29], v0, off offset:96
	v_mov_b32_e32 v0, v123
	s_nop 0
	v_lshlrev_b32_e32 v0, 16, v0
	v_mul_f32_e32 v4, 0xbfb8aa3b, v0
	v_exp_f32_e32 v4, v4
	s_nop 0
	v_add_f32_e32 v4, 1.0, v4
	v_div_scale_f32 v5, s[0:1], v4, v4, v0
	v_rcp_f32_e32 v7, v5
	v_div_scale_f32 v6, vcc, v0, v4, v0
	v_fma_f32 v10, -v5, v7, 1.0
	v_fmac_f32_e32 v7, v10, v7
	v_mul_f32_e32 v10, v6, v7
	v_fma_f32 v11, -v5, v10, v6
	v_fmac_f32_e32 v10, v11, v7
	v_fma_f32 v5, -v5, v10, v6
	v_div_fmas_f32 v5, v5, v7, v10
	v_div_fixup_f32 v0, v5, v4, v0
	v_mul_f32_e32 v0, v1, v0
	v_cvt_pk_bf16_f32 v0, v0, s0
	global_store_short v[32:33], v0, off offset:96
	v_mov_b32_e32 v0, v124
	v_mul_f32_e32 v1, v2, v49
	v_mul_f32_e32 v1, v41, v1
	s_nop 0
	v_lshlrev_b32_e32 v0, 16, v0
	v_mul_f32_e32 v2, 0xbfb8aa3b, v0
	v_exp_f32_e32 v2, v2
	s_nop 0
	v_add_f32_e32 v2, 1.0, v2
	v_div_scale_f32 v4, s[0:1], v2, v2, v0
	v_rcp_f32_e32 v6, v4
	v_div_scale_f32 v5, vcc, v0, v2, v0
	v_fma_f32 v7, -v4, v6, 1.0
	v_fmac_f32_e32 v6, v7, v6
	v_mul_f32_e32 v7, v5, v6
	v_fma_f32 v10, -v4, v7, v5
	v_fmac_f32_e32 v7, v10, v6
	v_fma_f32 v4, -v4, v7, v5
	v_div_fmas_f32 v4, v4, v6, v7
	v_div_fixup_f32 v0, v4, v2, v0
	v_mul_f32_e32 v0, v1, v0
	v_cvt_pk_bf16_f32 v0, v0, s0
	global_store_short v[30:31], v0, off offset:96
	v_mov_b32_e32 v0, v125
	v_mul_f32_e32 v1, v3, v36
	v_mul_f32_e32 v1, v41, v1
	s_nop 0
	v_lshlrev_b32_e32 v0, 16, v0
	v_mul_f32_e32 v2, 0xbfb8aa3b, v0
	v_exp_f32_e32 v2, v2
	s_nop 0
	v_add_f32_e32 v2, 1.0, v2
	v_div_scale_f32 v3, s[0:1], v2, v2, v0
	v_rcp_f32_e32 v4, v3
	v_div_scale_f32 v5, vcc, v0, v2, v0
	v_fma_f32 v6, -v3, v4, 1.0
	v_fmac_f32_e32 v4, v6, v4
	v_mul_f32_e32 v6, v5, v4
	v_fma_f32 v7, -v3, v6, v5
	v_fmac_f32_e32 v6, v7, v4
	v_fma_f32 v3, -v3, v6, v5
	v_div_fmas_f32 v3, v3, v4, v6
	v_div_fixup_f32 v0, v3, v2, v0
	v_mul_f32_e32 v0, v1, v0
	v_cvt_pk_bf16_f32 v0, v0, s0
	global_store_short v[12:13], v0, off offset:96
	s_cbranch_scc1 .LBB0_542

; __device__ __forceinline__ uint2 pack4v(f32x4 a) { uint2 r; r.x = pack2(a[0], a[1]); r.y = pack2(a[2], a[3]); return r; }
; __device__ void ph_gemm2(const P& p, u16* lds) {
;     ...
;     const f32x4 g4 = *(const f32x4*)(p.norm_ffn + nt * 128 + wn * 64 + (lane & 15) * 4);
;     gemm_epilogue(acc, lds, [](int, int, int, float v) { return v; },
;       [&](int rowl, int c4, f32x4 v) {
;         const int m = mt * 128 + wm * 64 + rowl, n = nt * 128 + wn * 64 + c4 * 4;
;         const f32x4 hv = *(const f32x4*)(xrow(p, m) + n) + v;
;         *(uint2*)(p_h16 + (size_t)m * DM + n) = pack4v(hv);
;         *(uint2*)(p_Abf + (size_t)m * DM + n) = pack4v(hv * g4);
;         const float part = row16_sum(hv[0] * hv[0] + hv[1] * hv[1] + hv[2] * hv[2] + hv[3] * hv[3]);
;         if (c4 == 0) atomicAdd(p_ssq2 + m, part);
;       });
.LBB0_605:
	s_and_b32 s81, s27, 7
	s_lshr_b32 s82, s27, 3
	s_lshr_b32 s83, s82, 6
	s_and_b32 s84, s82, 63
	s_cmp_lt_u32 s83, 4
	s_cselect_b32 s85, 3, 0
	s_cselect_b32 s86, 7, 0
	s_lshr_b32 s87, s84, s85
	s_and_b32 s84, s84, s86
	s_lshl_b32 s83, s83, 3
	s_add_u32 s83, s83, s84
	s_mul_i32 s81, s81, 33
	s_add_u32 s81, s81, s83
	s_mul_i32 s81, s81, 8
	s_add_u32 s27, s81, s87
	s_ashr_i32 s0, s27, 31
	s_lshr_b32 s0, s0, 29
	s_add_i32 s28, s27, s0
	s_and_b32 s0, s28, 0x1fffff8
	s_sub_i32 s0, s27, s0
	s_lshl_b32 s0, s0, 7
	s_ashr_i32 s1, s0, 31
	v_lshl_add_u64 v[0:1], s[0:1], 2, v[78:79]
	v_mov_b32_e32 v68, v220
	global_load_dwordx4 v[0:3], v[0:1], off
	s_lshl_b32 s1, s28, 4
	v_and_b32_e32 v95, 15, v68
	v_bfe_u32 v68, v68, 4, 2
	s_and_b32 s27, s1, 0xffffff80
	v_or_b32_e32 v80, s27, v68
	v_add_u32_e32 v82, v80, v87
	v_readlane_b32 s36, v228, 17
	v_add_u32_e32 v81, 0xffff8000, v82
	v_cmp_gt_i32_e32 vcc, s22, v82
	v_readlane_b32 s37, v228, 18
	v_readlane_b32 s39, v228, 20
	v_ashrrev_i32_e32 v83, 31, v82
	v_cndmask_b32_e32 v84, v81, v82, vcc
	v_readlane_b32 s38, v228, 19
	v_mov_b32_e32 v81, s39
	v_mov_b32_e32 v88, s37
	v_lshlrev_b32_e32 v96, 2, v95
	v_cndmask_b32_e32 v85, 0, v83, vcc
	v_cndmask_b32_e32 v89, v81, v88, vcc
	v_mov_b32_e32 v81, s38
	v_mov_b32_e32 v88, s36
	v_or3_b32 v80, s0, v86, v96
	v_cndmask_b32_e32 v88, v81, v88, vcc
	v_lshlrev_b64 v[84:85], 12, v[84:85]
	v_lshl_add_u64 v[84:85], v[88:89], 0, v[84:85]
	v_ashrrev_i32_e32 v81, 31, v80
	v_mov_b32_e32 v94, v220
	v_lshl_add_u64 v[84:85], v[80:81], 2, v[84:85]
	global_load_dwordx4 v[90:93], v[84:85], off
	s_mov_b64 s[96:97], 0x4000
	v_lshl_add_u64 v[208:209], v[84:85], 0, s[96:97]
	global_load_dwordx4 v[148:151], v[208:209], off
	v_lshl_add_u64 v[208:209], v[208:209], 0, s[96:97]
	global_load_dwordx4 v[152:155], v[208:209], off
	v_lshl_add_u64 v[208:209], v[208:209], 0, s[96:97]
	global_load_dwordx4 v[156:159], v[208:209], off
	v_lshl_add_u64 v[208:209], v[208:209], 0, s[96:97]
	global_load_dwordx4 v[160:163], v[208:209], off
	v_lshl_add_u64 v[208:209], v[208:209], 0, s[96:97]
	global_load_dwordx4 v[164:167], v[208:209], off
	v_lshl_add_u64 v[208:209], v[208:209], 0, s[96:97]
	global_load_dwordx4 v[168:171], v[208:209], off
	v_lshl_add_u64 v[208:209], v[208:209], 0, s[96:97]
	global_load_dwordx4 v[172:175], v[208:209], off
	v_lshl_add_u64 v[208:209], v[208:209], 0, s[96:97]
	global_load_dwordx4 v[176:179], v[208:209], off
	v_lshl_add_u64 v[208:209], v[208:209], 0, s[96:97]
	global_load_dwordx4 v[180:183], v[208:209], off
	v_lshl_add_u64 v[208:209], v[208:209], 0, s[96:97]
	global_load_dwordx4 v[184:187], v[208:209], off
	v_lshl_add_u64 v[208:209], v[208:209], 0, s[96:97]
	global_load_dwordx4 v[188:191], v[208:209], off
	v_lshl_add_u64 v[208:209], v[208:209], 0, s[96:97]
	global_load_dwordx4 v[192:195], v[208:209], off
	v_lshl_add_u64 v[208:209], v[208:209], 0, s[96:97]
	global_load_dwordx4 v[196:199], v[208:209], off
	v_lshl_add_u64 v[208:209], v[208:209], 0, s[96:97]
	global_load_dwordx4 v[200:203], v[208:209], off
	v_lshl_add_u64 v[208:209], v[208:209], 0, s[96:97]
	global_load_dwordx4 v[204:207], v[208:209], off
	v_lshrrev_b32_e32 v84, 6, v94
	v_mul_lo_u32 v84, v84, s23
	v_or_b32_e32 v88, v84, v96
	v_mad_u32_u24 v84, v68, s24, v88
	v_mad_u32_u24 v89, v95, 12, v88
	v_add_u32_e32 v96, 0x8000, v84
	v_mad_u32_u24 v97, v68, s25, v89
	ds_write2_b32 v96, v52, v60 offset1:16
	ds_write2_b32 v96, v53, v61 offset0:68 offset1:84
	ds_write2_b32 v96, v54, v62 offset0:136 offset1:152
	ds_write2_b32 v96, v55, v63 offset0:204 offset1:220
	ds_write2_b32 v96, v56, v64 offset0:32 offset1:48
	ds_write2_b32 v96, v57, v65 offset0:100 offset1:116
	ds_write2_b32 v96, v58, v66 offset0:168 offset1:184
	ds_write2_b32 v96, v59, v67 offset0:236 offset1:252
	ds_read_b128 v[52:55], v97 offset:32768
	v_cmp_eq_u32_e32 vcc, 0, v95
	v_lshlrev_b64 v[94:95], 11, v[82:83]
	v_lshlrev_b64 v[84:85], 1, v[80:81]
	v_lshl_add_u64 v[56:57], s[2:3], 0, v[94:95]
	v_lshl_add_u64 v[58:59], s[4:5], 0, v[94:95]
	v_lshl_add_u64 v[56:57], v[56:57], 0, v[84:85]
	v_lshl_add_u64 v[58:59], v[58:59], 0, v[84:85]
	v_readlane_b32 s40, v228, 21
	v_readlane_b32 s41, v228, 22
	v_readlane_b32 s42, v228, 23
	v_readlane_b32 s43, v228, 24
	v_readlane_b32 s44, v228, 25
	v_readlane_b32 s45, v228, 26
	v_readlane_b32 s46, v228, 27
	v_readlane_b32 s47, v228, 28
	v_readlane_b32 s48, v228, 29
	v_readlane_b32 s49, v228, 30
	v_readlane_b32 s50, v228, 31
	v_readlane_b32 s51, v228, 32
	s_waitcnt vmcnt(0) lgkmcnt(0)
	v_pk_add_f32 v[52:53], v[52:53], v[90:91]
	s_nop 0
	v_cvt_pk_bf16_f32 v60, v52, v53
	v_pk_mul_f32 v[64:65], v[0:1], v[52:53]
	v_mul_f32_e32 v53, v53, v53
	v_pk_add_f32 v[54:55], v[54:55], v[92:93]
	v_fmac_f32_e32 v53, v52, v52
	v_fmac_f32_e32 v53, v54, v54
	v_fmac_f32_e32 v53, v55, v55
	v_cvt_pk_bf16_f32 v61, v54, v55
	v_pk_mul_f32 v[62:63], v[2:3], v[54:55]
	v_add_f32_dpp v52, v53, v53 quad_perm:[1,0,3,2] row_mask:0xf bank_mask:0xf bound_ctrl:1
	global_store_dwordx2 v[56:57], v[60:61], off
	v_cvt_pk_bf16_f32 v56, v64, v65
	v_add_f32_dpp v52, v52, v52 quad_perm:[2,3,0,1] row_mask:0xf bank_mask:0xf bound_ctrl:1
	v_cvt_pk_bf16_f32 v57, v62, v63
	global_store_dwordx2 v[58:59], v[56:57], off
	v_add_f32_dpp v52, v52, v52 row_half_mirror row_mask:0xf bank_mask:0xf bound_ctrl:1
	s_nop 1
	v_mov_b32_dpp v53, v52 row_mirror row_mask:0xf bank_mask:0xf bound_ctrl:1
	s_and_saveexec_b64 s[0:1], vcc
	s_cbranch_execz .LBB0_607
	v_lshl_add_u64 v[54:55], v[82:83], 2, s[6:7]
	v_add_f32_e32 v52, v52, v53
	global_atomic_add_f32 v[54:55], v52, off
; __device__ __forceinline__ uint2 pack4v(f32x4 a) { uint2 r; r.x = pack2(a[0], a[1]); r.y = pack2(a[2], a[3]); return r; }
; __device__ void ph_gemm2(const P& p, u16* lds) {
;     ...
;         const int m = mt * 128 + wm * 64 + rowl, n = nt * 128 + wn * 64 + c4 * 4;
;         const f32x4 hv = *(const f32x4*)(xrow(p, m) + n) + v;
;         *(uint2*)(p_h16 + (size_t)m * DM + n) = pack4v(hv);
;         *(uint2*)(p_Abf + (size_t)m * DM + n) = pack4v(hv * g4);
;         const float part = row16_sum(hv[0] * hv[0] + hv[1] * hv[1] + hv[2] * hv[2] + hv[3] * hv[3]);
;         if (c4 == 0) atomicAdd(p_ssq2 + m, part);
.LBB0_607:
	s_or_b64 exec, exec, s[0:1]
	v_or3_b32 v52, v68, s27, 4
	v_readlane_b32 s36, v228, 17
	v_add_u32_e32 v52, v52, v87
	v_readlane_b32 s37, v228, 18
	v_readlane_b32 s39, v228, 20
	v_add_u32_e32 v54, 0xffff8000, v52
	v_ashrrev_i32_e32 v53, 31, v52
	v_cmp_gt_i32_e64 s[0:1], s22, v52
	v_readlane_b32 s38, v228, 19
	v_mov_b32_e32 v56, s39
	v_mov_b32_e32 v57, s37
	v_cndmask_b32_e64 v55, 0, v53, s[0:1]
	v_cndmask_b32_e64 v54, v54, v52, s[0:1]
	v_cndmask_b32_e64 v57, v56, v57, s[0:1]
	v_mov_b32_e32 v56, s38
	v_mov_b32_e32 v58, s36
	v_cndmask_b32_e64 v56, v56, v58, s[0:1]
	v_lshlrev_b64 v[54:55], 12, v[54:55]
	v_lshl_add_u64 v[54:55], v[56:57], 0, v[54:55]
	v_lshl_add_u64 v[54:55], v[80:81], 2, v[54:55]
	v_mov_b32_e32 v56, v148
	v_mov_b32_e32 v57, v149
	v_mov_b32_e32 v58, v150
	v_mov_b32_e32 v59, v151
	v_mul_u32_u24_e32 v54, 0x110, v68
	v_add_u32_e32 v54, v54, v89
	ds_read_b128 v[60:63], v54 offset:33856
	v_lshlrev_b64 v[64:65], 11, v[52:53]
	v_lshl_add_u64 v[66:67], s[2:3], 0, v[64:65]
	v_lshl_add_u64 v[64:65], s[4:5], 0, v[64:65]
	v_lshl_add_u64 v[66:67], v[66:67], 0, v[84:85]
	v_lshl_add_u64 v[64:65], v[64:65], 0, v[84:85]
	v_readlane_b32 s40, v228, 21
	v_readlane_b32 s41, v228, 22
	v_readlane_b32 s42, v228, 23
	v_readlane_b32 s43, v228, 24
	v_readlane_b32 s44, v228, 25
	v_readlane_b32 s45, v228, 26
	v_readlane_b32 s46, v228, 27
	v_readlane_b32 s47, v228, 28
	v_readlane_b32 s48, v228, 29
	v_readlane_b32 s49, v228, 30
	v_readlane_b32 s50, v228, 31
	v_readlane_b32 s51, v228, 32
	s_waitcnt lgkmcnt(0)
	v_pk_add_f32 v[56:57], v[60:61], v[56:57]
	s_nop 0
	v_mul_f32_e32 v55, v57, v57
	v_pk_add_f32 v[58:59], v[62:63], v[58:59]
	v_fmac_f32_e32 v55, v56, v56
	v_fmac_f32_e32 v55, v58, v58
	v_fmac_f32_e32 v55, v59, v59
	v_cvt_pk_bf16_f32 v60, v56, v57
	v_cvt_pk_bf16_f32 v61, v58, v59
	v_add_f32_dpp v55, v55, v55 quad_perm:[1,0,3,2] row_mask:0xf bank_mask:0xf bound_ctrl:1
	v_pk_mul_f32 v[62:63], v[2:3], v[58:59]
	v_pk_mul_f32 v[90:91], v[0:1], v[56:57]
	v_add_f32_dpp v55, v55, v55 quad_perm:[2,3,0,1] row_mask:0xf bank_mask:0xf bound_ctrl:1
	global_store_dwordx2 v[66:67], v[60:61], off
	v_cvt_pk_bf16_f32 v60, v90, v91
	v_add_f32_dpp v55, v55, v55 row_half_mirror row_mask:0xf bank_mask:0xf bound_ctrl:1
	v_cvt_pk_bf16_f32 v61, v62, v63
	global_store_dwordx2 v[64:65], v[60:61], off
	v_mov_b32_dpp v56, v55 row_mirror row_mask:0xf bank_mask:0xf bound_ctrl:1
	s_and_saveexec_b64 s[0:1], vcc
	s_cbranch_execz .LBB0_609
	v_lshl_add_u64 v[52:53], v[52:53], 2, s[6:7]
	v_add_f32_e32 v55, v55, v56
	global_atomic_add_f32 v[52:53], v55, off
.LBB0_609:
	s_or_b64 exec, exec, s[0:1]
	v_or3_b32 v52, v68, s27, 8
	v_add_u32_e32 v52, v52, v87
	v_readlane_b32 s36, v228, 17
	v_add_u32_e32 v55, 0xffff8000, v52
	v_cmp_gt_i32_e64 s[0:1], s22, v52
	v_readlane_b32 s37, v228, 18
	v_readlane_b32 s39, v228, 20
	v_ashrrev_i32_e32 v53, 31, v52
	v_cndmask_b32_e64 v56, v55, v52, s[0:1]
	v_readlane_b32 s38, v228, 19
	v_mov_b32_e32 v55, s39
	v_mov_b32_e32 v58, s37
	v_cndmask_b32_e64 v57, 0, v53, s[0:1]
	v_cndmask_b32_e64 v59, v55, v58, s[0:1]
	v_mov_b32_e32 v55, s38
	v_mov_b32_e32 v58, s36
	v_cndmask_b32_e64 v58, v55, v58, s[0:1]
	v_lshlrev_b64 v[56:57], 12, v[56:57]
	v_lshl_add_u64 v[56:57], v[58:59], 0, v[56:57]
	v_lshl_add_u64 v[56:57], v[80:81], 2, v[56:57]
	v_mov_b32_e32 v56, v152
	v_mov_b32_e32 v57, v153
	v_mov_b32_e32 v58, v154
	v_mov_b32_e32 v59, v155
	ds_read_b128 v[60:63], v54 offset:34944
	v_lshlrev_b64 v[64:65], 11, v[52:53]
	v_lshl_add_u64 v[66:67], s[2:3], 0, v[64:65]
	v_lshl_add_u64 v[64:65], s[4:5], 0, v[64:65]
	v_lshl_add_u64 v[66:67], v[66:67], 0, v[84:85]
	v_lshl_add_u64 v[64:65], v[64:65], 0, v[84:85]
	v_readlane_b32 s40, v228, 21
	v_readlane_b32 s41, v228, 22
	v_readlane_b32 s42, v228, 23
	v_readlane_b32 s43, v228, 24
	v_readlane_b32 s44, v228, 25
	v_readlane_b32 s45, v228, 26
	v_readlane_b32 s46, v228, 27
	v_readlane_b32 s47, v228, 28
	v_readlane_b32 s48, v228, 29
	v_readlane_b32 s49, v228, 30
	v_readlane_b32 s50, v228, 31
	v_readlane_b32 s51, v228, 32
	s_waitcnt lgkmcnt(0)
	v_pk_add_f32 v[56:57], v[60:61], v[56:57]
	s_nop 0
	v_mul_f32_e32 v55, v57, v57
	v_pk_add_f32 v[58:59], v[62:63], v[58:59]
	v_fmac_f32_e32 v55, v56, v56
	v_fmac_f32_e32 v55, v58, v58
	v_fmac_f32_e32 v55, v59, v59
	v_cvt_pk_bf16_f32 v60, v56, v57
	v_cvt_pk_bf16_f32 v61, v58, v59
	v_add_f32_dpp v55, v55, v55 quad_perm:[1,0,3,2] row_mask:0xf bank_mask:0xf bound_ctrl:1
	v_pk_mul_f32 v[62:63], v[2:3], v[58:59]
	v_pk_mul_f32 v[90:91], v[0:1], v[56:57]
	v_add_f32_dpp v55, v55, v55 quad_perm:[2,3,0,1] row_mask:0xf bank_mask:0xf bound_ctrl:1
	global_store_dwordx2 v[66:67], v[60:61], off
	v_cvt_pk_bf16_f32 v60, v90, v91
	v_add_f32_dpp v55, v55, v55 row_half_mirror row_mask:0xf bank_mask:0xf bound_ctrl:1
	v_cvt_pk_bf16_f32 v61, v62, v63
	global_store_dwordx2 v[64:65], v[60:61], off
	v_mov_b32_dpp v56, v55 row_mirror row_mask:0xf bank_mask:0xf bound_ctrl:1
	s_and_saveexec_b64 s[0:1], vcc
	s_cbranch_execz .LBB0_611
	v_lshl_add_u64 v[52:53], v[52:53], 2, s[6:7]
	v_add_f32_e32 v55, v55, v56
	global_atomic_add_f32 v[52:53], v55, off
; __device__ __forceinline__ uint2 pack4v(f32x4 a) { uint2 r; r.x = pack2(a[0], a[1]); r.y = pack2(a[2], a[3]); return r; }
; template <typename PRE, typename OUT>
; __device__ __forceinline__ void gemm_epilogue(f32x4 (&acc)[4][4], u16* lds, PRE pre, OUT out) {
;     ...
;       for (int r = 0; r < 4; ++r) W[(fq * 4 + r) * EPS_STRIDE + j * 16 + fr] = pre(i, j, r, acc[i][j][r]);
; #pragma unroll
;     for (int q = 0; q < 4; ++q) {
;       const int row = q * 4 + (lane >> 4), c4 = lane & 15;
;       const f32x4 v = *(const f32x4*)(W + row * EPS_STRIDE + c4 * 4);
;       out(i * 16 + row, c4, v);
; __device__ void ph_gemm2(const P& p, u16* lds) {
;     ...
;         const int m = mt * 128 + wm * 64 + rowl, n = nt * 128 + wn * 64 + c4 * 4;
;         const f32x4 hv = *(const f32x4*)(xrow(p, m) + n) + v;
;         *(uint2*)(p_h16 + (size_t)m * DM + n) = pack4v(hv);
;         *(uint2*)(p_Abf + (size_t)m * DM + n) = pack4v(hv * g4);
;         const float part = row16_sum(hv[0] * hv[0] + hv[1] * hv[1] + hv[2] * hv[2] + hv[3] * hv[3]);
;         if (c4 == 0) atomicAdd(p_ssq2 + m, part);
.LBB0_611:
	s_or_b64 exec, exec, s[0:1]
	v_or3_b32 v52, v68, s27, 12
	v_add_u32_e32 v52, v52, v87
	v_readlane_b32 s36, v228, 17
	v_add_u32_e32 v55, 0xffff8000, v52
	v_cmp_gt_i32_e64 s[0:1], s22, v52
	v_readlane_b32 s37, v228, 18
	v_readlane_b32 s39, v228, 20
	v_ashrrev_i32_e32 v53, 31, v52
	v_cndmask_b32_e64 v56, v55, v52, s[0:1]
	v_readlane_b32 s38, v228, 19
	v_mov_b32_e32 v55, s39
	v_mov_b32_e32 v58, s37
	v_cndmask_b32_e64 v57, 0, v53, s[0:1]
	v_cndmask_b32_e64 v59, v55, v58, s[0:1]
	v_mov_b32_e32 v55, s38
	v_mov_b32_e32 v58, s36
	v_cndmask_b32_e64 v58, v55, v58, s[0:1]
	v_lshlrev_b64 v[56:57], 12, v[56:57]
	v_lshl_add_u64 v[56:57], v[58:59], 0, v[56:57]
	v_lshl_add_u64 v[56:57], v[80:81], 2, v[56:57]
	v_mov_b32_e32 v56, v156
	v_mov_b32_e32 v57, v157
	v_mov_b32_e32 v58, v158
	v_mov_b32_e32 v59, v159
	ds_read_b128 v[60:63], v54 offset:36032
	v_lshlrev_b64 v[64:65], 11, v[52:53]
	v_lshl_add_u64 v[66:67], s[2:3], 0, v[64:65]
	v_lshl_add_u64 v[64:65], s[4:5], 0, v[64:65]
	v_lshl_add_u64 v[66:67], v[66:67], 0, v[84:85]
	v_lshl_add_u64 v[64:65], v[64:65], 0, v[84:85]
	v_readlane_b32 s40, v228, 21
	v_readlane_b32 s41, v228, 22
	v_readlane_b32 s42, v228, 23
	v_readlane_b32 s43, v228, 24
	v_readlane_b32 s44, v228, 25
	v_readlane_b32 s45, v228, 26
	v_readlane_b32 s46, v228, 27
	v_readlane_b32 s47, v228, 28
	v_readlane_b32 s48, v228, 29
	v_readlane_b32 s49, v228, 30
	v_readlane_b32 s50, v228, 31
	v_readlane_b32 s51, v228, 32
	s_waitcnt lgkmcnt(0)
	v_pk_add_f32 v[56:57], v[60:61], v[56:57]
	s_nop 0
	v_mul_f32_e32 v55, v57, v57
	v_pk_add_f32 v[58:59], v[62:63], v[58:59]
	v_fmac_f32_e32 v55, v56, v56
	v_fmac_f32_e32 v55, v58, v58
	v_fmac_f32_e32 v55, v59, v59
	v_cvt_pk_bf16_f32 v60, v56, v57
	v_cvt_pk_bf16_f32 v61, v58, v59
	v_add_f32_dpp v55, v55, v55 quad_perm:[1,0,3,2] row_mask:0xf bank_mask:0xf bound_ctrl:1
	v_pk_mul_f32 v[62:63], v[2:3], v[58:59]
	v_pk_mul_f32 v[90:91], v[0:1], v[56:57]
	v_add_f32_dpp v55, v55, v55 quad_perm:[2,3,0,1] row_mask:0xf bank_mask:0xf bound_ctrl:1
	global_store_dwordx2 v[66:67], v[60:61], off
	v_cvt_pk_bf16_f32 v60, v90, v91
	v_add_f32_dpp v55, v55, v55 row_half_mirror row_mask:0xf bank_mask:0xf bound_ctrl:1
	v_cvt_pk_bf16_f32 v61, v62, v63
	global_store_dwordx2 v[64:65], v[60:61], off
	v_mov_b32_dpp v56, v55 row_mirror row_mask:0xf bank_mask:0xf bound_ctrl:1
	s_and_saveexec_b64 s[0:1], vcc
	s_cbranch_execz .LBB0_613
	v_lshl_add_u64 v[52:53], v[52:53], 2, s[6:7]
	v_add_f32_e32 v55, v55, v56
	global_atomic_add_f32 v[52:53], v55, off
.LBB0_613:
	s_or_b64 exec, exec, s[0:1]
	v_add_u32_e32 v52, 16, v82
	v_readlane_b32 s36, v228, 17
	v_add_u32_e32 v55, 0xffff8010, v82
	v_cmp_gt_i32_e64 s[0:1], s22, v52
	v_readlane_b32 s37, v228, 18
	v_readlane_b32 s39, v228, 20
	v_ashrrev_i32_e32 v53, 31, v52
	v_cndmask_b32_e64 v56, v55, v52, s[0:1]
	v_readlane_b32 s38, v228, 19
	v_mov_b32_e32 v55, s39
	v_mov_b32_e32 v58, s37
	v_cndmask_b32_e64 v57, 0, v53, s[0:1]
	v_cndmask_b32_e64 v59, v55, v58, s[0:1]
	v_mov_b32_e32 v55, s38
	v_mov_b32_e32 v58, s36
	v_cndmask_b32_e64 v58, v55, v58, s[0:1]
	v_lshlrev_b64 v[56:57], 12, v[56:57]
	v_lshl_add_u64 v[56:57], v[58:59], 0, v[56:57]
	v_lshl_add_u64 v[56:57], v[80:81], 2, v[56:57]
	v_mov_b32_e32 v56, v160
	v_mov_b32_e32 v57, v161
	v_mov_b32_e32 v58, v162
	v_mov_b32_e32 v59, v163
	v_mul_u32_u24_e32 v55, 0x440, v68
	v_add_u32_e32 v55, v88, v55
	v_add_u32_e32 v55, 0x8000, v55
	ds_write2_b32 v55, v44, v48 offset1:16
	ds_write2_b32 v55, v45, v49 offset0:68 offset1:84
	ds_write2_b32 v55, v46, v50 offset0:136 offset1:152
	ds_write2_b32 v55, v47, v51 offset0:204 offset1:220
	ds_write2_b32 v55, v36, v40 offset0:32 offset1:48
	ds_write2_b32 v55, v37, v41 offset0:100 offset1:116
	ds_write2_b32 v55, v38, v42 offset0:168 offset1:184
	ds_write2_b32 v55, v39, v43 offset0:236 offset1:252
	ds_read_b128 v[36:39], v54 offset:32768
	v_lshlrev_b64 v[60:61], 11, v[52:53]
	v_lshl_add_u64 v[40:41], s[2:3], 0, v[60:61]
	v_lshl_add_u64 v[42:43], s[4:5], 0, v[60:61]
	v_lshl_add_u64 v[40:41], v[40:41], 0, v[84:85]
	v_lshl_add_u64 v[42:43], v[42:43], 0, v[84:85]
	v_readlane_b32 s40, v228, 21
	v_readlane_b32 s41, v228, 22
	v_readlane_b32 s42, v228, 23
	v_readlane_b32 s43, v228, 24
	v_readlane_b32 s44, v228, 25
	v_readlane_b32 s45, v228, 26
	v_readlane_b32 s46, v228, 27
	v_readlane_b32 s47, v228, 28
	v_readlane_b32 s48, v228, 29
	v_readlane_b32 s49, v228, 30
	v_readlane_b32 s50, v228, 31
	v_readlane_b32 s51, v228, 32
	s_waitcnt lgkmcnt(0)
	v_pk_add_f32 v[36:37], v[36:37], v[56:57]
	s_nop 0
	v_cvt_pk_bf16_f32 v44, v36, v37
	v_pk_mul_f32 v[48:49], v[0:1], v[36:37]
	v_mul_f32_e32 v37, v37, v37
	v_pk_add_f32 v[38:39], v[38:39], v[58:59]
	v_fmac_f32_e32 v37, v36, v36
	v_fmac_f32_e32 v37, v38, v38
	v_fmac_f32_e32 v37, v39, v39
	v_cvt_pk_bf16_f32 v45, v38, v39
	v_pk_mul_f32 v[46:47], v[2:3], v[38:39]
	v_add_f32_dpp v36, v37, v37 quad_perm:[1,0,3,2] row_mask:0xf bank_mask:0xf bound_ctrl:1
	global_store_dwordx2 v[40:41], v[44:45], off
	v_cvt_pk_bf16_f32 v40, v48, v49
	v_add_f32_dpp v36, v36, v36 quad_perm:[2,3,0,1] row_mask:0xf bank_mask:0xf bound_ctrl:1
	v_cvt_pk_bf16_f32 v41, v46, v47
	global_store_dwordx2 v[42:43], v[40:41], off
	v_add_f32_dpp v36, v36, v36 row_half_mirror row_mask:0xf bank_mask:0xf bound_ctrl:1
	s_nop 1
	v_mov_b32_dpp v37, v36 row_mirror row_mask:0xf bank_mask:0xf bound_ctrl:1
	s_and_saveexec_b64 s[0:1], vcc
	s_cbranch_execz .LBB0_615
	v_lshl_add_u64 v[38:39], v[52:53], 2, s[6:7]
	v_add_f32_e32 v36, v36, v37
	global_atomic_add_f32 v[38:39], v36, off
; __device__ __forceinline__ uint2 pack4v(f32x4 a) { uint2 r; r.x = pack2(a[0], a[1]); r.y = pack2(a[2], a[3]); return r; }
; __device__ void ph_gemm2(const P& p, u16* lds) {
;     ...
;         const int m = mt * 128 + wm * 64 + rowl, n = nt * 128 + wn * 64 + c4 * 4;
;         const f32x4 hv = *(const f32x4*)(xrow(p, m) + n) + v;
;         *(uint2*)(p_h16 + (size_t)m * DM + n) = pack4v(hv);
;         *(uint2*)(p_Abf + (size_t)m * DM + n) = pack4v(hv * g4);
;         const float part = row16_sum(hv[0] * hv[0] + hv[1] * hv[1] + hv[2] * hv[2] + hv[3] * hv[3]);
;         if (c4 == 0) atomicAdd(p_ssq2 + m, part);
.LBB0_615:
	s_or_b64 exec, exec, s[0:1]
	v_readlane_b32 s36, v228, 17
	v_add_u32_e32 v36, 20, v82
	v_readlane_b32 s37, v228, 18
	v_readlane_b32 s39, v228, 20
	v_add_u32_e32 v38, 0xffff8014, v82
	v_ashrrev_i32_e32 v37, 31, v36
	v_cmp_gt_i32_e64 s[0:1], s22, v36
	v_readlane_b32 s38, v228, 19
	v_mov_b32_e32 v40, s39
	v_mov_b32_e32 v41, s37
	v_cndmask_b32_e64 v39, 0, v37, s[0:1]
	v_cndmask_b32_e64 v38, v38, v36, s[0:1]
	v_cndmask_b32_e64 v41, v40, v41, s[0:1]
	v_mov_b32_e32 v40, s38
	v_mov_b32_e32 v42, s36
	v_cndmask_b32_e64 v40, v40, v42, s[0:1]
	v_lshlrev_b64 v[38:39], 12, v[38:39]
	v_lshl_add_u64 v[38:39], v[40:41], 0, v[38:39]
	v_lshl_add_u64 v[38:39], v[80:81], 2, v[38:39]
	v_mov_b32_e32 v38, v164
	v_mov_b32_e32 v39, v165
	v_mov_b32_e32 v40, v166
	v_mov_b32_e32 v41, v167
	ds_read_b128 v[42:45], v54 offset:33856
	v_lshlrev_b64 v[46:47], 11, v[36:37]
	v_lshl_add_u64 v[48:49], s[2:3], 0, v[46:47]
	v_lshl_add_u64 v[46:47], s[4:5], 0, v[46:47]
	v_lshl_add_u64 v[48:49], v[48:49], 0, v[84:85]
	v_lshl_add_u64 v[46:47], v[46:47], 0, v[84:85]
	v_readlane_b32 s40, v228, 21
	v_readlane_b32 s41, v228, 22
	v_readlane_b32 s42, v228, 23
	v_readlane_b32 s43, v228, 24
	v_readlane_b32 s44, v228, 25
	v_readlane_b32 s45, v228, 26
	v_readlane_b32 s46, v228, 27
	v_readlane_b32 s47, v228, 28
	v_readlane_b32 s48, v228, 29
	v_readlane_b32 s49, v228, 30
	v_readlane_b32 s50, v228, 31
	v_readlane_b32 s51, v228, 32
	s_waitcnt lgkmcnt(0)
	v_pk_add_f32 v[38:39], v[42:43], v[38:39]
	s_nop 0
	v_cvt_pk_bf16_f32 v42, v38, v39
	v_pk_mul_f32 v[50:51], v[0:1], v[38:39]
	v_mul_f32_e32 v39, v39, v39
	v_pk_add_f32 v[40:41], v[44:45], v[40:41]
	v_fmac_f32_e32 v39, v38, v38
	v_fmac_f32_e32 v39, v40, v40
	v_fmac_f32_e32 v39, v41, v41
	v_cvt_pk_bf16_f32 v43, v40, v41
	v_pk_mul_f32 v[44:45], v[2:3], v[40:41]
	v_add_f32_dpp v38, v39, v39 quad_perm:[1,0,3,2] row_mask:0xf bank_mask:0xf bound_ctrl:1
	global_store_dwordx2 v[48:49], v[42:43], off
	v_cvt_pk_bf16_f32 v42, v50, v51
	v_add_f32_dpp v38, v38, v38 quad_perm:[2,3,0,1] row_mask:0xf bank_mask:0xf bound_ctrl:1
	v_cvt_pk_bf16_f32 v43, v44, v45
	global_store_dwordx2 v[46:47], v[42:43], off
	v_add_f32_dpp v38, v38, v38 row_half_mirror row_mask:0xf bank_mask:0xf bound_ctrl:1
	s_nop 1
	v_mov_b32_dpp v39, v38 row_mirror row_mask:0xf bank_mask:0xf bound_ctrl:1
	s_and_saveexec_b64 s[0:1], vcc
	s_cbranch_execz .LBB0_617
	v_lshl_add_u64 v[36:37], v[36:37], 2, s[6:7]
	v_add_f32_e32 v38, v38, v39
	global_atomic_add_f32 v[36:37], v38, off
.LBB0_617:
	s_or_b64 exec, exec, s[0:1]
	v_readlane_b32 s36, v228, 17
	v_add_u32_e32 v36, 24, v82
	v_readlane_b32 s37, v228, 18
	v_readlane_b32 s39, v228, 20
	v_add_u32_e32 v38, 0xffff8018, v82
	v_ashrrev_i32_e32 v37, 31, v36
	v_cmp_gt_i32_e64 s[0:1], s22, v36
	v_readlane_b32 s38, v228, 19
	v_mov_b32_e32 v40, s39
	v_mov_b32_e32 v41, s37
	v_cndmask_b32_e64 v39, 0, v37, s[0:1]
	v_cndmask_b32_e64 v38, v38, v36, s[0:1]
	v_cndmask_b32_e64 v41, v40, v41, s[0:1]
	v_mov_b32_e32 v40, s38
	v_mov_b32_e32 v42, s36
	v_cndmask_b32_e64 v40, v40, v42, s[0:1]
	v_lshlrev_b64 v[38:39], 12, v[38:39]
	v_lshl_add_u64 v[38:39], v[40:41], 0, v[38:39]
	v_lshl_add_u64 v[38:39], v[80:81], 2, v[38:39]
	v_mov_b32_e32 v38, v168
	v_mov_b32_e32 v39, v169
	v_mov_b32_e32 v40, v170
	v_mov_b32_e32 v41, v171
	ds_read_b128 v[42:45], v54 offset:34944
	v_lshlrev_b64 v[46:47], 11, v[36:37]
	v_lshl_add_u64 v[48:49], s[2:3], 0, v[46:47]
	v_lshl_add_u64 v[46:47], s[4:5], 0, v[46:47]
	v_lshl_add_u64 v[48:49], v[48:49], 0, v[84:85]
	v_lshl_add_u64 v[46:47], v[46:47], 0, v[84:85]
	v_readlane_b32 s40, v228, 21
	v_readlane_b32 s41, v228, 22
	v_readlane_b32 s42, v228, 23
	v_readlane_b32 s43, v228, 24
	v_readlane_b32 s44, v228, 25
	v_readlane_b32 s45, v228, 26
	v_readlane_b32 s46, v228, 27
	v_readlane_b32 s47, v228, 28
	v_readlane_b32 s48, v228, 29
	v_readlane_b32 s49, v228, 30
	v_readlane_b32 s50, v228, 31
	v_readlane_b32 s51, v228, 32
	s_waitcnt lgkmcnt(0)
	v_pk_add_f32 v[38:39], v[42:43], v[38:39]
	s_nop 0
	v_cvt_pk_bf16_f32 v42, v38, v39
	v_pk_mul_f32 v[50:51], v[0:1], v[38:39]
	v_mul_f32_e32 v39, v39, v39
	v_pk_add_f32 v[40:41], v[44:45], v[40:41]
	v_fmac_f32_e32 v39, v38, v38
	v_fmac_f32_e32 v39, v40, v40
	v_fmac_f32_e32 v39, v41, v41
	v_cvt_pk_bf16_f32 v43, v40, v41
	v_pk_mul_f32 v[44:45], v[2:3], v[40:41]
	v_add_f32_dpp v38, v39, v39 quad_perm:[1,0,3,2] row_mask:0xf bank_mask:0xf bound_ctrl:1
	global_store_dwordx2 v[48:49], v[42:43], off
	v_cvt_pk_bf16_f32 v42, v50, v51
	v_add_f32_dpp v38, v38, v38 quad_perm:[2,3,0,1] row_mask:0xf bank_mask:0xf bound_ctrl:1
	v_cvt_pk_bf16_f32 v43, v44, v45
	global_store_dwordx2 v[46:47], v[42:43], off
	v_add_f32_dpp v38, v38, v38 row_half_mirror row_mask:0xf bank_mask:0xf bound_ctrl:1
	s_nop 1
	v_mov_b32_dpp v39, v38 row_mirror row_mask:0xf bank_mask:0xf bound_ctrl:1
	s_and_saveexec_b64 s[0:1], vcc
	s_cbranch_execz .LBB0_619
	v_lshl_add_u64 v[36:37], v[36:37], 2, s[6:7]
	v_add_f32_e32 v38, v38, v39
	global_atomic_add_f32 v[36:37], v38, off
; __device__ __forceinline__ uint2 pack4v(f32x4 a) { uint2 r; r.x = pack2(a[0], a[1]); r.y = pack2(a[2], a[3]); return r; }
; template <typename PRE, typename OUT>
; __device__ __forceinline__ void gemm_epilogue(f32x4 (&acc)[4][4], u16* lds, PRE pre, OUT out) {
;     ...
;       for (int r = 0; r < 4; ++r) W[(fq * 4 + r) * EPS_STRIDE + j * 16 + fr] = pre(i, j, r, acc[i][j][r]);
; #pragma unroll
;     for (int q = 0; q < 4; ++q) {
;       const int row = q * 4 + (lane >> 4), c4 = lane & 15;
;       const f32x4 v = *(const f32x4*)(W + row * EPS_STRIDE + c4 * 4);
;       out(i * 16 + row, c4, v);
; __device__ void ph_gemm2(const P& p, u16* lds) {
;     ...
;         const int m = mt * 128 + wm * 64 + rowl, n = nt * 128 + wn * 64 + c4 * 4;
;         const f32x4 hv = *(const f32x4*)(xrow(p, m) + n) + v;
;         *(uint2*)(p_h16 + (size_t)m * DM + n) = pack4v(hv);
;         *(uint2*)(p_Abf + (size_t)m * DM + n) = pack4v(hv * g4);
;         const float part = row16_sum(hv[0] * hv[0] + hv[1] * hv[1] + hv[2] * hv[2] + hv[3] * hv[3]);
;         if (c4 == 0) atomicAdd(p_ssq2 + m, part);
.LBB0_619:
	s_or_b64 exec, exec, s[0:1]
	v_readlane_b32 s36, v228, 17
	v_add_u32_e32 v36, 28, v82
	v_readlane_b32 s37, v228, 18
	v_readlane_b32 s39, v228, 20
	v_add_u32_e32 v38, 0xffff801c, v82
	v_ashrrev_i32_e32 v37, 31, v36
	v_cmp_gt_i32_e64 s[0:1], s22, v36
	v_readlane_b32 s38, v228, 19
	v_mov_b32_e32 v40, s39
	v_mov_b32_e32 v41, s37
	v_cndmask_b32_e64 v39, 0, v37, s[0:1]
	v_cndmask_b32_e64 v38, v38, v36, s[0:1]
	v_cndmask_b32_e64 v41, v40, v41, s[0:1]
	v_mov_b32_e32 v40, s38
	v_mov_b32_e32 v42, s36
	v_cndmask_b32_e64 v40, v40, v42, s[0:1]
	v_lshlrev_b64 v[38:39], 12, v[38:39]
	v_lshl_add_u64 v[38:39], v[40:41], 0, v[38:39]
	v_lshl_add_u64 v[38:39], v[80:81], 2, v[38:39]
	v_mov_b32_e32 v38, v172
	v_mov_b32_e32 v39, v173
	v_mov_b32_e32 v40, v174
	v_mov_b32_e32 v41, v175
	ds_read_b128 v[42:45], v54 offset:36032
	v_lshlrev_b64 v[46:47], 11, v[36:37]
	v_lshl_add_u64 v[48:49], s[2:3], 0, v[46:47]
	v_lshl_add_u64 v[46:47], s[4:5], 0, v[46:47]
	v_lshl_add_u64 v[48:49], v[48:49], 0, v[84:85]
	v_lshl_add_u64 v[46:47], v[46:47], 0, v[84:85]
	v_readlane_b32 s40, v228, 21
	v_readlane_b32 s41, v228, 22
	v_readlane_b32 s42, v228, 23
	v_readlane_b32 s43, v228, 24
	v_readlane_b32 s44, v228, 25
	v_readlane_b32 s45, v228, 26
	v_readlane_b32 s46, v228, 27
	v_readlane_b32 s47, v228, 28
	v_readlane_b32 s48, v228, 29
	v_readlane_b32 s49, v228, 30
	v_readlane_b32 s50, v228, 31
	v_readlane_b32 s51, v228, 32
	s_waitcnt lgkmcnt(0)
	v_pk_add_f32 v[38:39], v[42:43], v[38:39]
	s_nop 0
	v_cvt_pk_bf16_f32 v42, v38, v39
	v_pk_mul_f32 v[50:51], v[0:1], v[38:39]
	v_mul_f32_e32 v39, v39, v39
	v_pk_add_f32 v[40:41], v[44:45], v[40:41]
	v_fmac_f32_e32 v39, v38, v38
	v_fmac_f32_e32 v39, v40, v40
	v_fmac_f32_e32 v39, v41, v41
	v_cvt_pk_bf16_f32 v43, v40, v41
	v_pk_mul_f32 v[44:45], v[2:3], v[40:41]
	v_add_f32_dpp v38, v39, v39 quad_perm:[1,0,3,2] row_mask:0xf bank_mask:0xf bound_ctrl:1
	global_store_dwordx2 v[48:49], v[42:43], off
	v_cvt_pk_bf16_f32 v42, v50, v51
	v_add_f32_dpp v38, v38, v38 quad_perm:[2,3,0,1] row_mask:0xf bank_mask:0xf bound_ctrl:1
	v_cvt_pk_bf16_f32 v43, v44, v45
	global_store_dwordx2 v[46:47], v[42:43], off
	v_add_f32_dpp v38, v38, v38 row_half_mirror row_mask:0xf bank_mask:0xf bound_ctrl:1
	s_nop 1
	v_mov_b32_dpp v39, v38 row_mirror row_mask:0xf bank_mask:0xf bound_ctrl:1
	s_and_saveexec_b64 s[0:1], vcc
	s_cbranch_execz .LBB0_621
	v_lshl_add_u64 v[36:37], v[36:37], 2, s[6:7]
	v_add_f32_e32 v38, v38, v39
	global_atomic_add_f32 v[36:37], v38, off
.LBB0_621:
	s_or_b64 exec, exec, s[0:1]
	v_readlane_b32 s36, v228, 17
	v_add_u32_e32 v36, 32, v82
	v_readlane_b32 s37, v228, 18
	v_readlane_b32 s39, v228, 20
	v_add_u32_e32 v38, 0xffff8020, v82
	v_ashrrev_i32_e32 v37, 31, v36
	v_cmp_gt_i32_e64 s[0:1], s22, v36
	v_readlane_b32 s38, v228, 19
	v_mov_b32_e32 v40, s39
	v_mov_b32_e32 v41, s37
	v_cndmask_b32_e64 v39, 0, v37, s[0:1]
	v_cndmask_b32_e64 v38, v38, v36, s[0:1]
	v_cndmask_b32_e64 v41, v40, v41, s[0:1]
	v_mov_b32_e32 v40, s38
	v_mov_b32_e32 v42, s36
	v_cndmask_b32_e64 v40, v40, v42, s[0:1]
	v_lshlrev_b64 v[38:39], 12, v[38:39]
	v_lshl_add_u64 v[38:39], v[40:41], 0, v[38:39]
	v_lshl_add_u64 v[38:39], v[80:81], 2, v[38:39]
	v_mov_b32_e32 v38, v176
	v_mov_b32_e32 v39, v177
	v_mov_b32_e32 v40, v178
	v_mov_b32_e32 v41, v179
	ds_write2_b32 v55, v28, v32 offset1:16
	ds_write2_b32 v55, v29, v33 offset0:68 offset1:84
	ds_write2_b32 v55, v30, v34 offset0:136 offset1:152
	ds_write2_b32 v55, v31, v35 offset0:204 offset1:220
	ds_write2_b32 v55, v20, v24 offset0:32 offset1:48
	ds_write2_b32 v55, v21, v25 offset0:100 offset1:116
	ds_write2_b32 v55, v22, v26 offset0:168 offset1:184
	ds_write2_b32 v55, v23, v27 offset0:236 offset1:252
	ds_read_b128 v[20:23], v54 offset:32768
	v_lshlrev_b64 v[24:25], 11, v[36:37]
	v_lshl_add_u64 v[26:27], s[2:3], 0, v[24:25]
	v_lshl_add_u64 v[24:25], s[4:5], 0, v[24:25]
	v_lshl_add_u64 v[26:27], v[26:27], 0, v[84:85]
	v_lshl_add_u64 v[24:25], v[24:25], 0, v[84:85]
	v_readlane_b32 s40, v228, 21
	v_readlane_b32 s41, v228, 22
	v_readlane_b32 s42, v228, 23
	v_readlane_b32 s43, v228, 24
	v_readlane_b32 s44, v228, 25
	v_readlane_b32 s45, v228, 26
	v_readlane_b32 s46, v228, 27
	v_readlane_b32 s47, v228, 28
	v_readlane_b32 s48, v228, 29
	v_readlane_b32 s49, v228, 30
	v_readlane_b32 s50, v228, 31
	v_readlane_b32 s51, v228, 32
	s_waitcnt lgkmcnt(0)
	v_pk_add_f32 v[20:21], v[20:21], v[38:39]
	s_nop 0
	v_cvt_pk_bf16_f32 v28, v20, v21
	v_pk_mul_f32 v[32:33], v[0:1], v[20:21]
	v_mul_f32_e32 v21, v21, v21
	v_pk_add_f32 v[22:23], v[22:23], v[40:41]
	v_fmac_f32_e32 v21, v20, v20
	v_fmac_f32_e32 v21, v22, v22
	v_fmac_f32_e32 v21, v23, v23
	v_cvt_pk_bf16_f32 v29, v22, v23
	v_pk_mul_f32 v[30:31], v[2:3], v[22:23]
	v_add_f32_dpp v20, v21, v21 quad_perm:[1,0,3,2] row_mask:0xf bank_mask:0xf bound_ctrl:1
	global_store_dwordx2 v[26:27], v[28:29], off
	v_cvt_pk_bf16_f32 v26, v32, v33
	v_add_f32_dpp v20, v20, v20 quad_perm:[2,3,0,1] row_mask:0xf bank_mask:0xf bound_ctrl:1
	v_cvt_pk_bf16_f32 v27, v30, v31
	global_store_dwordx2 v[24:25], v[26:27], off
	v_add_f32_dpp v20, v20, v20 row_half_mirror row_mask:0xf bank_mask:0xf bound_ctrl:1
	s_nop 1
	v_mov_b32_dpp v21, v20 row_mirror row_mask:0xf bank_mask:0xf bound_ctrl:1
	s_and_saveexec_b64 s[0:1], vcc
	s_cbranch_execz .LBB0_623
	v_lshl_add_u64 v[22:23], v[36:37], 2, s[6:7]
	v_add_f32_e32 v20, v20, v21
	global_atomic_add_f32 v[22:23], v20, off
; __device__ __forceinline__ uint2 pack4v(f32x4 a) { uint2 r; r.x = pack2(a[0], a[1]); r.y = pack2(a[2], a[3]); return r; }
; __device__ void ph_gemm2(const P& p, u16* lds) {
;     ...
;         const int m = mt * 128 + wm * 64 + rowl, n = nt * 128 + wn * 64 + c4 * 4;
;         const f32x4 hv = *(const f32x4*)(xrow(p, m) + n) + v;
;         *(uint2*)(p_h16 + (size_t)m * DM + n) = pack4v(hv);
;         *(uint2*)(p_Abf + (size_t)m * DM + n) = pack4v(hv * g4);
;         const float part = row16_sum(hv[0] * hv[0] + hv[1] * hv[1] + hv[2] * hv[2] + hv[3] * hv[3]);
;         if (c4 == 0) atomicAdd(p_ssq2 + m, part);
.LBB0_623:
	s_or_b64 exec, exec, s[0:1]
	v_readlane_b32 s36, v228, 17
	v_add_u32_e32 v20, 36, v82
	v_readlane_b32 s37, v228, 18
	v_readlane_b32 s39, v228, 20
	v_add_u32_e32 v22, 0xffff8024, v82
	v_ashrrev_i32_e32 v21, 31, v20
	v_cmp_gt_i32_e64 s[0:1], s22, v20
	v_readlane_b32 s38, v228, 19
	v_mov_b32_e32 v24, s39
	v_mov_b32_e32 v25, s37
	v_cndmask_b32_e64 v23, 0, v21, s[0:1]
	v_cndmask_b32_e64 v22, v22, v20, s[0:1]
	v_cndmask_b32_e64 v25, v24, v25, s[0:1]
	v_mov_b32_e32 v24, s38
	v_mov_b32_e32 v26, s36
	v_cndmask_b32_e64 v24, v24, v26, s[0:1]
	v_lshlrev_b64 v[22:23], 12, v[22:23]
	v_lshl_add_u64 v[22:23], v[24:25], 0, v[22:23]
	v_lshl_add_u64 v[22:23], v[80:81], 2, v[22:23]
	v_mov_b32_e32 v22, v180
	v_mov_b32_e32 v23, v181
	v_mov_b32_e32 v24, v182
	v_mov_b32_e32 v25, v183
	ds_read_b128 v[26:29], v54 offset:33856
	v_lshlrev_b64 v[30:31], 11, v[20:21]
	v_lshl_add_u64 v[32:33], s[2:3], 0, v[30:31]
	v_lshl_add_u64 v[30:31], s[4:5], 0, v[30:31]
	v_lshl_add_u64 v[32:33], v[32:33], 0, v[84:85]
	v_lshl_add_u64 v[30:31], v[30:31], 0, v[84:85]
	v_readlane_b32 s40, v228, 21
	v_readlane_b32 s41, v228, 22
	v_readlane_b32 s42, v228, 23
	v_readlane_b32 s43, v228, 24
	v_readlane_b32 s44, v228, 25
	v_readlane_b32 s45, v228, 26
	v_readlane_b32 s46, v228, 27
	v_readlane_b32 s47, v228, 28
	v_readlane_b32 s48, v228, 29
	v_readlane_b32 s49, v228, 30
	v_readlane_b32 s50, v228, 31
	v_readlane_b32 s51, v228, 32
	s_waitcnt lgkmcnt(0)
	v_pk_add_f32 v[22:23], v[26:27], v[22:23]
	s_nop 0
	v_cvt_pk_bf16_f32 v26, v22, v23
	v_pk_mul_f32 v[34:35], v[0:1], v[22:23]
	v_mul_f32_e32 v23, v23, v23
	v_pk_add_f32 v[24:25], v[28:29], v[24:25]
	v_fmac_f32_e32 v23, v22, v22
	v_fmac_f32_e32 v23, v24, v24
	v_fmac_f32_e32 v23, v25, v25
	v_cvt_pk_bf16_f32 v27, v24, v25
	v_pk_mul_f32 v[28:29], v[2:3], v[24:25]
	v_add_f32_dpp v22, v23, v23 quad_perm:[1,0,3,2] row_mask:0xf bank_mask:0xf bound_ctrl:1
	global_store_dwordx2 v[32:33], v[26:27], off
	v_cvt_pk_bf16_f32 v26, v34, v35
	v_add_f32_dpp v22, v22, v22 quad_perm:[2,3,0,1] row_mask:0xf bank_mask:0xf bound_ctrl:1
	v_cvt_pk_bf16_f32 v27, v28, v29
	global_store_dwordx2 v[30:31], v[26:27], off
	v_add_f32_dpp v22, v22, v22 row_half_mirror row_mask:0xf bank_mask:0xf bound_ctrl:1
	s_nop 1
	v_mov_b32_dpp v23, v22 row_mirror row_mask:0xf bank_mask:0xf bound_ctrl:1
	s_and_saveexec_b64 s[0:1], vcc
	s_cbranch_execz .LBB0_625
	v_lshl_add_u64 v[20:21], v[20:21], 2, s[6:7]
	v_add_f32_e32 v22, v22, v23
	global_atomic_add_f32 v[20:21], v22, off
.LBB0_625:
	s_or_b64 exec, exec, s[0:1]
	v_readlane_b32 s36, v228, 17
	v_add_u32_e32 v20, 40, v82
	v_readlane_b32 s37, v228, 18
	v_readlane_b32 s39, v228, 20
	v_add_u32_e32 v22, 0xffff8028, v82
	v_ashrrev_i32_e32 v21, 31, v20
	v_cmp_gt_i32_e64 s[0:1], s22, v20
	v_readlane_b32 s38, v228, 19
	v_mov_b32_e32 v24, s39
	v_mov_b32_e32 v25, s37
	v_cndmask_b32_e64 v23, 0, v21, s[0:1]
	v_cndmask_b32_e64 v22, v22, v20, s[0:1]
	v_cndmask_b32_e64 v25, v24, v25, s[0:1]
	v_mov_b32_e32 v24, s38
	v_mov_b32_e32 v26, s36
	v_cndmask_b32_e64 v24, v24, v26, s[0:1]
	v_lshlrev_b64 v[22:23], 12, v[22:23]
	v_lshl_add_u64 v[22:23], v[24:25], 0, v[22:23]
	v_lshl_add_u64 v[22:23], v[80:81], 2, v[22:23]
	v_mov_b32_e32 v22, v184
	v_mov_b32_e32 v23, v185
	v_mov_b32_e32 v24, v186
	v_mov_b32_e32 v25, v187
	ds_read_b128 v[26:29], v54 offset:34944
	v_lshlrev_b64 v[30:31], 11, v[20:21]
	v_lshl_add_u64 v[32:33], s[2:3], 0, v[30:31]
	v_lshl_add_u64 v[30:31], s[4:5], 0, v[30:31]
	v_lshl_add_u64 v[32:33], v[32:33], 0, v[84:85]
	v_lshl_add_u64 v[30:31], v[30:31], 0, v[84:85]
	v_readlane_b32 s40, v228, 21
	v_readlane_b32 s41, v228, 22
	v_readlane_b32 s42, v228, 23
	v_readlane_b32 s43, v228, 24
	v_readlane_b32 s44, v228, 25
	v_readlane_b32 s45, v228, 26
	v_readlane_b32 s46, v228, 27
	v_readlane_b32 s47, v228, 28
	v_readlane_b32 s48, v228, 29
	v_readlane_b32 s49, v228, 30
	v_readlane_b32 s50, v228, 31
	v_readlane_b32 s51, v228, 32
	s_waitcnt lgkmcnt(0)
	v_pk_add_f32 v[22:23], v[26:27], v[22:23]
	s_nop 0
	v_cvt_pk_bf16_f32 v26, v22, v23
	v_pk_mul_f32 v[34:35], v[0:1], v[22:23]
	v_mul_f32_e32 v23, v23, v23
	v_pk_add_f32 v[24:25], v[28:29], v[24:25]
	v_fmac_f32_e32 v23, v22, v22
	v_fmac_f32_e32 v23, v24, v24
	v_fmac_f32_e32 v23, v25, v25
	v_cvt_pk_bf16_f32 v27, v24, v25
	v_pk_mul_f32 v[28:29], v[2:3], v[24:25]
	v_add_f32_dpp v22, v23, v23 quad_perm:[1,0,3,2] row_mask:0xf bank_mask:0xf bound_ctrl:1
	global_store_dwordx2 v[32:33], v[26:27], off
	v_cvt_pk_bf16_f32 v26, v34, v35
	v_add_f32_dpp v22, v22, v22 quad_perm:[2,3,0,1] row_mask:0xf bank_mask:0xf bound_ctrl:1
	v_cvt_pk_bf16_f32 v27, v28, v29
	global_store_dwordx2 v[30:31], v[26:27], off
	v_add_f32_dpp v22, v22, v22 row_half_mirror row_mask:0xf bank_mask:0xf bound_ctrl:1
	s_nop 1
	v_mov_b32_dpp v23, v22 row_mirror row_mask:0xf bank_mask:0xf bound_ctrl:1
	s_and_saveexec_b64 s[0:1], vcc
	s_cbranch_execz .LBB0_627
	v_lshl_add_u64 v[20:21], v[20:21], 2, s[6:7]
	v_add_f32_e32 v22, v22, v23
	global_atomic_add_f32 v[20:21], v22, off
; __device__ __forceinline__ uint2 pack4v(f32x4 a) { uint2 r; r.x = pack2(a[0], a[1]); r.y = pack2(a[2], a[3]); return r; }
; template <typename PRE, typename OUT>
; __device__ __forceinline__ void gemm_epilogue(f32x4 (&acc)[4][4], u16* lds, PRE pre, OUT out) {
;     ...
;       for (int r = 0; r < 4; ++r) W[(fq * 4 + r) * EPS_STRIDE + j * 16 + fr] = pre(i, j, r, acc[i][j][r]);
; #pragma unroll
;     for (int q = 0; q < 4; ++q) {
;       const int row = q * 4 + (lane >> 4), c4 = lane & 15;
;       const f32x4 v = *(const f32x4*)(W + row * EPS_STRIDE + c4 * 4);
;       out(i * 16 + row, c4, v);
; __device__ void ph_gemm2(const P& p, u16* lds) {
;     ...
;         const int m = mt * 128 + wm * 64 + rowl, n = nt * 128 + wn * 64 + c4 * 4;
;         const f32x4 hv = *(const f32x4*)(xrow(p, m) + n) + v;
;         *(uint2*)(p_h16 + (size_t)m * DM + n) = pack4v(hv);
;         *(uint2*)(p_Abf + (size_t)m * DM + n) = pack4v(hv * g4);
;         const float part = row16_sum(hv[0] * hv[0] + hv[1] * hv[1] + hv[2] * hv[2] + hv[3] * hv[3]);
;         if (c4 == 0) atomicAdd(p_ssq2 + m, part);
.LBB0_627:
	s_or_b64 exec, exec, s[0:1]
	v_readlane_b32 s36, v228, 17
	v_add_u32_e32 v20, 44, v82
	v_readlane_b32 s37, v228, 18
	v_readlane_b32 s39, v228, 20
	v_add_u32_e32 v22, 0xffff802c, v82
	v_ashrrev_i32_e32 v21, 31, v20
	v_cmp_gt_i32_e64 s[0:1], s22, v20
	v_readlane_b32 s38, v228, 19
	v_mov_b32_e32 v24, s39
	v_mov_b32_e32 v25, s37
	v_cndmask_b32_e64 v23, 0, v21, s[0:1]
	v_cndmask_b32_e64 v22, v22, v20, s[0:1]
	v_cndmask_b32_e64 v25, v24, v25, s[0:1]
	v_mov_b32_e32 v24, s38
	v_mov_b32_e32 v26, s36
	v_cndmask_b32_e64 v24, v24, v26, s[0:1]
	v_lshlrev_b64 v[22:23], 12, v[22:23]
	v_lshl_add_u64 v[22:23], v[24:25], 0, v[22:23]
	v_lshl_add_u64 v[22:23], v[80:81], 2, v[22:23]
	v_mov_b32_e32 v22, v188
	v_mov_b32_e32 v23, v189
	v_mov_b32_e32 v24, v190
	v_mov_b32_e32 v25, v191
	ds_read_b128 v[26:29], v54 offset:36032
	v_lshlrev_b64 v[30:31], 11, v[20:21]
	v_lshl_add_u64 v[32:33], s[2:3], 0, v[30:31]
	v_lshl_add_u64 v[30:31], s[4:5], 0, v[30:31]
	v_lshl_add_u64 v[32:33], v[32:33], 0, v[84:85]
	v_lshl_add_u64 v[30:31], v[30:31], 0, v[84:85]
	v_readlane_b32 s40, v228, 21
	v_readlane_b32 s41, v228, 22
	v_readlane_b32 s42, v228, 23
	v_readlane_b32 s43, v228, 24
	v_readlane_b32 s44, v228, 25
	v_readlane_b32 s45, v228, 26
	v_readlane_b32 s46, v228, 27
	v_readlane_b32 s47, v228, 28
	v_readlane_b32 s48, v228, 29
	v_readlane_b32 s49, v228, 30
	v_readlane_b32 s50, v228, 31
	v_readlane_b32 s51, v228, 32
	s_waitcnt lgkmcnt(0)
	v_pk_add_f32 v[22:23], v[26:27], v[22:23]
	s_nop 0
	v_cvt_pk_bf16_f32 v26, v22, v23
	v_pk_mul_f32 v[34:35], v[0:1], v[22:23]
	v_mul_f32_e32 v23, v23, v23
	v_pk_add_f32 v[24:25], v[28:29], v[24:25]
	v_fmac_f32_e32 v23, v22, v22
	v_fmac_f32_e32 v23, v24, v24
	v_fmac_f32_e32 v23, v25, v25
	v_cvt_pk_bf16_f32 v27, v24, v25
	v_pk_mul_f32 v[28:29], v[2:3], v[24:25]
	v_add_f32_dpp v22, v23, v23 quad_perm:[1,0,3,2] row_mask:0xf bank_mask:0xf bound_ctrl:1
	global_store_dwordx2 v[32:33], v[26:27], off
	v_cvt_pk_bf16_f32 v26, v34, v35
	v_add_f32_dpp v22, v22, v22 quad_perm:[2,3,0,1] row_mask:0xf bank_mask:0xf bound_ctrl:1
	v_cvt_pk_bf16_f32 v27, v28, v29
	global_store_dwordx2 v[30:31], v[26:27], off
	v_add_f32_dpp v22, v22, v22 row_half_mirror row_mask:0xf bank_mask:0xf bound_ctrl:1
	s_nop 1
	v_mov_b32_dpp v23, v22 row_mirror row_mask:0xf bank_mask:0xf bound_ctrl:1
	s_and_saveexec_b64 s[0:1], vcc
	s_cbranch_execz .LBB0_629
	v_lshl_add_u64 v[20:21], v[20:21], 2, s[6:7]
	v_add_f32_e32 v22, v22, v23
	global_atomic_add_f32 v[20:21], v22, off
.LBB0_629:
	s_or_b64 exec, exec, s[0:1]
	v_readlane_b32 s36, v228, 17
	v_add_u32_e32 v20, 48, v82
	v_readlane_b32 s37, v228, 18
	v_readlane_b32 s39, v228, 20
	v_add_u32_e32 v22, 0xffff8030, v82
	v_ashrrev_i32_e32 v21, 31, v20
	v_cmp_gt_i32_e64 s[0:1], s22, v20
	v_readlane_b32 s38, v228, 19
	v_mov_b32_e32 v24, s39
	v_mov_b32_e32 v25, s37
	v_cndmask_b32_e64 v23, 0, v21, s[0:1]
	v_cndmask_b32_e64 v22, v22, v20, s[0:1]
	v_cndmask_b32_e64 v25, v24, v25, s[0:1]
	v_mov_b32_e32 v24, s38
	v_mov_b32_e32 v26, s36
	v_cndmask_b32_e64 v24, v24, v26, s[0:1]
	v_lshlrev_b64 v[22:23], 12, v[22:23]
	v_lshl_add_u64 v[22:23], v[24:25], 0, v[22:23]
	v_lshl_add_u64 v[22:23], v[80:81], 2, v[22:23]
	v_mov_b32_e32 v22, v192
	v_mov_b32_e32 v23, v193
	v_mov_b32_e32 v24, v194
	v_mov_b32_e32 v25, v195
	ds_write2_b32 v55, v4, v8 offset1:16
	ds_write2_b32 v55, v5, v9 offset0:68 offset1:84
	ds_write2_b32 v55, v6, v10 offset0:136 offset1:152
	ds_write2_b32 v55, v7, v11 offset0:204 offset1:220
	ds_write2_b32 v55, v12, v16 offset0:32 offset1:48
	ds_write2_b32 v55, v13, v17 offset0:100 offset1:116
	ds_write2_b32 v55, v14, v18 offset0:168 offset1:184
	ds_write2_b32 v55, v15, v19 offset0:236 offset1:252
	ds_read_b128 v[4:7], v54 offset:32768
	v_lshlrev_b64 v[8:9], 11, v[20:21]
	v_lshl_add_u64 v[10:11], s[2:3], 0, v[8:9]
	v_lshl_add_u64 v[8:9], s[4:5], 0, v[8:9]
	v_lshl_add_u64 v[10:11], v[10:11], 0, v[84:85]
	v_lshl_add_u64 v[8:9], v[8:9], 0, v[84:85]
	v_readlane_b32 s40, v228, 21
	v_readlane_b32 s41, v228, 22
	v_readlane_b32 s42, v228, 23
	v_readlane_b32 s43, v228, 24
	v_readlane_b32 s44, v228, 25
	v_readlane_b32 s45, v228, 26
	v_readlane_b32 s46, v228, 27
	v_readlane_b32 s47, v228, 28
	v_readlane_b32 s48, v228, 29
	v_readlane_b32 s49, v228, 30
	v_readlane_b32 s50, v228, 31
	v_readlane_b32 s51, v228, 32
	s_waitcnt lgkmcnt(0)
	v_pk_add_f32 v[4:5], v[4:5], v[22:23]
	s_nop 0
	v_cvt_pk_bf16_f32 v12, v4, v5
	v_pk_mul_f32 v[16:17], v[0:1], v[4:5]
	v_mul_f32_e32 v5, v5, v5
	v_pk_add_f32 v[6:7], v[6:7], v[24:25]
	v_fmac_f32_e32 v5, v4, v4
	v_fmac_f32_e32 v5, v6, v6
	v_fmac_f32_e32 v5, v7, v7
	v_cvt_pk_bf16_f32 v13, v6, v7
	v_pk_mul_f32 v[14:15], v[2:3], v[6:7]
	v_add_f32_dpp v4, v5, v5 quad_perm:[1,0,3,2] row_mask:0xf bank_mask:0xf bound_ctrl:1
	global_store_dwordx2 v[10:11], v[12:13], off
	v_cvt_pk_bf16_f32 v10, v16, v17
	v_add_f32_dpp v4, v4, v4 quad_perm:[2,3,0,1] row_mask:0xf bank_mask:0xf bound_ctrl:1
	v_cvt_pk_bf16_f32 v11, v14, v15
	global_store_dwordx2 v[8:9], v[10:11], off
	v_add_f32_dpp v4, v4, v4 row_half_mirror row_mask:0xf bank_mask:0xf bound_ctrl:1
	s_nop 1
	v_mov_b32_dpp v5, v4 row_mirror row_mask:0xf bank_mask:0xf bound_ctrl:1
	s_and_saveexec_b64 s[0:1], vcc
	s_cbranch_execz .LBB0_631
	v_lshl_add_u64 v[6:7], v[20:21], 2, s[6:7]
	v_add_f32_e32 v4, v4, v5
	global_atomic_add_f32 v[6:7], v4, off
; __device__ __forceinline__ uint2 pack4v(f32x4 a) { uint2 r; r.x = pack2(a[0], a[1]); r.y = pack2(a[2], a[3]); return r; }
; __device__ void ph_gemm2(const P& p, u16* lds) {
;     ...
;         const int m = mt * 128 + wm * 64 + rowl, n = nt * 128 + wn * 64 + c4 * 4;
;         const f32x4 hv = *(const f32x4*)(xrow(p, m) + n) + v;
;         *(uint2*)(p_h16 + (size_t)m * DM + n) = pack4v(hv);
;         *(uint2*)(p_Abf + (size_t)m * DM + n) = pack4v(hv * g4);
;         const float part = row16_sum(hv[0] * hv[0] + hv[1] * hv[1] + hv[2] * hv[2] + hv[3] * hv[3]);
;         if (c4 == 0) atomicAdd(p_ssq2 + m, part);
.LBB0_631:
	s_or_b64 exec, exec, s[0:1]
	v_readlane_b32 s36, v228, 17
	v_add_u32_e32 v4, 52, v82
	v_readlane_b32 s37, v228, 18
	v_readlane_b32 s39, v228, 20
	v_add_u32_e32 v6, 0xffff8034, v82
	v_ashrrev_i32_e32 v5, 31, v4
	v_cmp_gt_i32_e64 s[0:1], s22, v4
	v_readlane_b32 s38, v228, 19
	v_mov_b32_e32 v8, s39
	v_mov_b32_e32 v9, s37
	v_cndmask_b32_e64 v7, 0, v5, s[0:1]
	v_cndmask_b32_e64 v6, v6, v4, s[0:1]
	v_cndmask_b32_e64 v9, v8, v9, s[0:1]
	v_mov_b32_e32 v8, s38
	v_mov_b32_e32 v10, s36
	v_cndmask_b32_e64 v8, v8, v10, s[0:1]
	v_lshlrev_b64 v[6:7], 12, v[6:7]
	v_lshl_add_u64 v[6:7], v[8:9], 0, v[6:7]
	v_lshl_add_u64 v[6:7], v[80:81], 2, v[6:7]
	v_mov_b32_e32 v6, v196
	v_mov_b32_e32 v7, v197
	v_mov_b32_e32 v8, v198
	v_mov_b32_e32 v9, v199
	ds_read_b128 v[10:13], v54 offset:33856
	v_lshlrev_b64 v[14:15], 11, v[4:5]
	v_lshl_add_u64 v[16:17], s[2:3], 0, v[14:15]
	v_lshl_add_u64 v[14:15], s[4:5], 0, v[14:15]
	v_lshl_add_u64 v[16:17], v[16:17], 0, v[84:85]
	v_lshl_add_u64 v[14:15], v[14:15], 0, v[84:85]
	v_readlane_b32 s40, v228, 21
	v_readlane_b32 s41, v228, 22
	v_readlane_b32 s42, v228, 23
	v_readlane_b32 s43, v228, 24
	v_readlane_b32 s44, v228, 25
	v_readlane_b32 s45, v228, 26
	v_readlane_b32 s46, v228, 27
	v_readlane_b32 s47, v228, 28
	v_readlane_b32 s48, v228, 29
	v_readlane_b32 s49, v228, 30
	v_readlane_b32 s50, v228, 31
	v_readlane_b32 s51, v228, 32
	s_waitcnt lgkmcnt(0)
	v_pk_add_f32 v[6:7], v[10:11], v[6:7]
	s_nop 0
	v_cvt_pk_bf16_f32 v10, v6, v7
	v_pk_mul_f32 v[18:19], v[0:1], v[6:7]
	v_mul_f32_e32 v7, v7, v7
	v_pk_add_f32 v[8:9], v[12:13], v[8:9]
	v_fmac_f32_e32 v7, v6, v6
	v_fmac_f32_e32 v7, v8, v8
	v_fmac_f32_e32 v7, v9, v9
	v_cvt_pk_bf16_f32 v11, v8, v9
	v_pk_mul_f32 v[12:13], v[2:3], v[8:9]
	v_add_f32_dpp v6, v7, v7 quad_perm:[1,0,3,2] row_mask:0xf bank_mask:0xf bound_ctrl:1
	global_store_dwordx2 v[16:17], v[10:11], off
	v_cvt_pk_bf16_f32 v10, v18, v19
	v_add_f32_dpp v6, v6, v6 quad_perm:[2,3,0,1] row_mask:0xf bank_mask:0xf bound_ctrl:1
	v_cvt_pk_bf16_f32 v11, v12, v13
	global_store_dwordx2 v[14:15], v[10:11], off
	v_add_f32_dpp v6, v6, v6 row_half_mirror row_mask:0xf bank_mask:0xf bound_ctrl:1
	s_nop 1
	v_mov_b32_dpp v7, v6 row_mirror row_mask:0xf bank_mask:0xf bound_ctrl:1
	s_and_saveexec_b64 s[0:1], vcc
	s_cbranch_execz .LBB0_633
	v_lshl_add_u64 v[4:5], v[4:5], 2, s[6:7]
	v_add_f32_e32 v6, v6, v7
	global_atomic_add_f32 v[4:5], v6, off
.LBB0_633:
	s_or_b64 exec, exec, s[0:1]
	v_readlane_b32 s36, v228, 17
	v_add_u32_e32 v4, 56, v82
	v_readlane_b32 s37, v228, 18
	v_readlane_b32 s39, v228, 20
	v_add_u32_e32 v6, 0xffff8038, v82
	v_ashrrev_i32_e32 v5, 31, v4
	v_cmp_gt_i32_e64 s[0:1], s22, v4
	v_readlane_b32 s38, v228, 19
	v_mov_b32_e32 v8, s39
	v_mov_b32_e32 v9, s37
	v_cndmask_b32_e64 v7, 0, v5, s[0:1]
	v_cndmask_b32_e64 v6, v6, v4, s[0:1]
	v_cndmask_b32_e64 v9, v8, v9, s[0:1]
	v_mov_b32_e32 v8, s38
	v_mov_b32_e32 v10, s36
	v_cndmask_b32_e64 v8, v8, v10, s[0:1]
	v_lshlrev_b64 v[6:7], 12, v[6:7]
	v_lshl_add_u64 v[6:7], v[8:9], 0, v[6:7]
	v_lshl_add_u64 v[6:7], v[80:81], 2, v[6:7]
	v_mov_b32_e32 v6, v200
	v_mov_b32_e32 v7, v201
	v_mov_b32_e32 v8, v202
	v_mov_b32_e32 v9, v203
	ds_read_b128 v[10:13], v54 offset:34944
	v_lshlrev_b64 v[14:15], 11, v[4:5]
	v_lshl_add_u64 v[16:17], s[2:3], 0, v[14:15]
	v_lshl_add_u64 v[14:15], s[4:5], 0, v[14:15]
	v_lshl_add_u64 v[16:17], v[16:17], 0, v[84:85]
	v_lshl_add_u64 v[14:15], v[14:15], 0, v[84:85]
	v_readlane_b32 s40, v228, 21
	v_readlane_b32 s41, v228, 22
	v_readlane_b32 s42, v228, 23
	v_readlane_b32 s43, v228, 24
	v_readlane_b32 s44, v228, 25
	v_readlane_b32 s45, v228, 26
	v_readlane_b32 s46, v228, 27
	v_readlane_b32 s47, v228, 28
	v_readlane_b32 s48, v228, 29
	v_readlane_b32 s49, v228, 30
	v_readlane_b32 s50, v228, 31
	v_readlane_b32 s51, v228, 32
	s_waitcnt lgkmcnt(0)
	v_pk_add_f32 v[6:7], v[10:11], v[6:7]
	s_nop 0
	v_cvt_pk_bf16_f32 v10, v6, v7
	v_pk_mul_f32 v[18:19], v[0:1], v[6:7]
	v_mul_f32_e32 v7, v7, v7
	v_pk_add_f32 v[8:9], v[12:13], v[8:9]
	v_fmac_f32_e32 v7, v6, v6
	v_fmac_f32_e32 v7, v8, v8
	v_fmac_f32_e32 v7, v9, v9
	v_cvt_pk_bf16_f32 v11, v8, v9
	v_pk_mul_f32 v[12:13], v[2:3], v[8:9]
	v_add_f32_dpp v6, v7, v7 quad_perm:[1,0,3,2] row_mask:0xf bank_mask:0xf bound_ctrl:1
	global_store_dwordx2 v[16:17], v[10:11], off
	v_cvt_pk_bf16_f32 v10, v18, v19
	v_add_f32_dpp v6, v6, v6 quad_perm:[2,3,0,1] row_mask:0xf bank_mask:0xf bound_ctrl:1
	v_cvt_pk_bf16_f32 v11, v12, v13
	global_store_dwordx2 v[14:15], v[10:11], off
	v_add_f32_dpp v6, v6, v6 row_half_mirror row_mask:0xf bank_mask:0xf bound_ctrl:1
	s_nop 1
	v_mov_b32_dpp v7, v6 row_mirror row_mask:0xf bank_mask:0xf bound_ctrl:1
	s_and_saveexec_b64 s[0:1], vcc
	s_cbranch_execz .LBB0_635
	v_lshl_add_u64 v[4:5], v[4:5], 2, s[6:7]
	v_add_f32_e32 v6, v6, v7
	global_atomic_add_f32 v[4:5], v6, off
; __device__ __forceinline__ uint2 pack4v(f32x4 a) { uint2 r; r.x = pack2(a[0], a[1]); r.y = pack2(a[2], a[3]); return r; }
; __device__ void ph_gemm2(const P& p, u16* lds) {
;     ...
;         const int m = mt * 128 + wm * 64 + rowl, n = nt * 128 + wn * 64 + c4 * 4;
;         const f32x4 hv = *(const f32x4*)(xrow(p, m) + n) + v;
;         *(uint2*)(p_h16 + (size_t)m * DM + n) = pack4v(hv);
;         *(uint2*)(p_Abf + (size_t)m * DM + n) = pack4v(hv * g4);
;         const float part = row16_sum(hv[0] * hv[0] + hv[1] * hv[1] + hv[2] * hv[2] + hv[3] * hv[3]);
;         if (c4 == 0) atomicAdd(p_ssq2 + m, part);
.LBB0_635:
	s_or_b64 exec, exec, s[0:1]
	v_readlane_b32 s36, v228, 17
	v_add_u32_e32 v4, 60, v82
	v_readlane_b32 s37, v228, 18
	v_readlane_b32 s39, v228, 20
	v_add_u32_e32 v6, 0xffff803c, v82
	v_ashrrev_i32_e32 v5, 31, v4
	v_cmp_gt_i32_e64 s[0:1], s22, v4
	v_readlane_b32 s38, v228, 19
	v_mov_b32_e32 v8, s39
	v_mov_b32_e32 v9, s37
	v_cndmask_b32_e64 v7, 0, v5, s[0:1]
	v_cndmask_b32_e64 v6, v6, v4, s[0:1]
	v_cndmask_b32_e64 v9, v8, v9, s[0:1]
	v_mov_b32_e32 v8, s38
	v_mov_b32_e32 v10, s36
	v_cndmask_b32_e64 v8, v8, v10, s[0:1]
	v_lshlrev_b64 v[6:7], 12, v[6:7]
	v_lshl_add_u64 v[6:7], v[8:9], 0, v[6:7]
	v_lshl_add_u64 v[6:7], v[80:81], 2, v[6:7]
	v_mov_b32_e32 v6, v204
	v_mov_b32_e32 v7, v205
	v_mov_b32_e32 v8, v206
	v_mov_b32_e32 v9, v207
	ds_read_b128 v[10:13], v54 offset:36032
	v_lshlrev_b64 v[14:15], 11, v[4:5]
	v_lshl_add_u64 v[16:17], s[2:3], 0, v[14:15]
	v_lshl_add_u64 v[14:15], s[4:5], 0, v[14:15]
	v_lshl_add_u64 v[14:15], v[14:15], 0, v[84:85]
	v_lshl_add_u64 v[16:17], v[16:17], 0, v[84:85]
	v_readlane_b32 s40, v228, 21
	v_readlane_b32 s41, v228, 22
	v_readlane_b32 s42, v228, 23
	v_readlane_b32 s43, v228, 24
	v_readlane_b32 s44, v228, 25
	v_readlane_b32 s45, v228, 26
	v_readlane_b32 s46, v228, 27
	v_readlane_b32 s47, v228, 28
	v_readlane_b32 s48, v228, 29
	v_readlane_b32 s49, v228, 30
	v_readlane_b32 s50, v228, 31
	v_readlane_b32 s51, v228, 32
	s_waitcnt lgkmcnt(0)
	v_pk_add_f32 v[6:7], v[10:11], v[6:7]
	s_nop 0
	v_cvt_pk_bf16_f32 v10, v6, v7
	v_pk_mul_f32 v[0:1], v[0:1], v[6:7]
	v_mul_f32_e32 v7, v7, v7
	v_pk_add_f32 v[8:9], v[12:13], v[8:9]
	v_fmac_f32_e32 v7, v6, v6
	v_pk_mul_f32 v[2:3], v[2:3], v[8:9]
	v_fmac_f32_e32 v7, v8, v8
	v_cvt_pk_bf16_f32 v0, v0, v1
	v_cvt_pk_bf16_f32 v1, v2, v3
	v_fmac_f32_e32 v7, v9, v9
	global_store_dwordx2 v[14:15], v[0:1], off
	v_cvt_pk_bf16_f32 v11, v8, v9
	v_add_f32_dpp v0, v7, v7 quad_perm:[1,0,3,2] row_mask:0xf bank_mask:0xf bound_ctrl:1
	global_store_dwordx2 v[16:17], v[10:11], off
	s_nop 0
	v_add_f32_dpp v0, v0, v0 quad_perm:[2,3,0,1] row_mask:0xf bank_mask:0xf bound_ctrl:1
	s_nop 1
	v_add_f32_dpp v0, v0, v0 row_half_mirror row_mask:0xf bank_mask:0xf bound_ctrl:1
	s_nop 1
	v_mov_b32_dpp v1, v0 row_mirror row_mask:0xf bank_mask:0xf bound_ctrl:1
	s_and_saveexec_b64 s[0:1], vcc
	s_cbranch_execz .LBB0_600
	v_lshl_add_u64 v[2:3], v[4:5], 2, s[6:7]
	v_add_f32_e32 v0, v0, v1
	global_atomic_add_f32 v[2:3], v0, off
	s_branch .LBB0_600

; __device__ __forceinline__ uint2 pack4v(f32x4 a) { uint2 r; r.x = pack2(a[0], a[1]); r.y = pack2(a[2], a[3]); return r; }
; __device__ void ph_gemm3(const P& p, u16* lds) {
;     ...
;     const int itn = it + gridDim.x; const bool more = itn < NTILES;
;     __syncthreads();
;     if (more) { g = ops(itn); gemm_prologue(g, lds); }
;     gemm_epilogue(acc, lds, [](int, int, int, float v) { return v; },
;       [&](int rowl, int c4, f32x4 v) {
;         const int m = mt * 128 + wm * 64 + rowl, n = nt * 128 + wn * 64 + c4 * 4;
;         const float rs = rsqrtf(p_ssq2[m] * (1.f / 1024.f) + EPS);
;         *(uint2*)(Qb + (size_t)m * 2048 + n) = pack4v(v * rs);
;       });
.LBB0_694:
	s_and_b32 s81, s23, 7
	s_lshr_b32 s82, s23, 3
	s_lshr_b32 s83, s82, 7
	s_and_b32 s84, s82, 127
	s_cmp_lt_u32 s83, 4
	s_cselect_b32 s85, 3, 0
	s_cselect_b32 s86, 7, 0
	s_lshr_b32 s87, s84, s85
	s_and_b32 s84, s84, s86
	s_lshl_b32 s83, s83, 3
	s_add_u32 s83, s83, s84
	s_mul_i32 s81, s81, 33
	s_add_u32 s81, s81, s83
	s_mul_i32 s81, s81, 16
	s_add_u32 s23, s81, s87
	s_ashr_i32 s24, s23, 31
	s_lshr_b32 s24, s24, 28
	s_add_i32 s24, s23, s24
	v_mov_b32_e32 v89, v220
	s_lshl_b32 s25, s24, 3
	s_and_b32 s25, s25, 0xffffff80
	v_bfe_u32 v95, v89, 4, 2
	v_or_b32_e32 v64, s25, v95
	v_add_u32_e32 v92, v64, v75
	v_ashrrev_i32_e32 v93, 31, v92
	v_mov_b32_e32 v94, v220
	v_lshl_add_u64 v[90:91], v[92:93], 2, s[2:3]
	global_load_dword v151, v[90:91], off offset:16
	global_load_dword v152, v[90:91], off offset:32
	global_load_dword v153, v[90:91], off offset:48
	global_load_dword v154, v[90:91], off offset:64
	global_load_dword v155, v[90:91], off offset:80
	global_load_dword v156, v[90:91], off offset:96
	global_load_dword v157, v[90:91], off offset:112
	global_load_dword v158, v[90:91], off offset:128
	global_load_dword v159, v[90:91], off offset:144
	global_load_dword v160, v[90:91], off offset:160
	global_load_dword v161, v[90:91], off offset:176
	global_load_dword v162, v[90:91], off offset:192
	global_load_dword v163, v[90:91], off offset:208
	global_load_dword v164, v[90:91], off offset:224
	global_load_dword v165, v[90:91], off offset:240
	global_load_dword v91, v[90:91], off
	v_lshrrev_b32_e32 v90, 6, v94
	v_and_b32_e32 v89, 15, v89
	v_mul_lo_u32 v90, v90, s18
	v_lshlrev_b32_e32 v94, 2, v89
	v_or_b32_e32 v90, v90, v94
	v_mad_u32_u24 v97, v89, 12, v90
	v_mad_u32_u24 v90, v95, s20, v90
	ds_write_b32 v90, v60 offset:32768
	ds_write_b32 v90, v61 offset:33040
	ds_write_b32 v90, v62 offset:33312
	ds_write_b32 v90, v63 offset:33584
	ds_write_b32 v90, v56 offset:32832
	ds_write_b32 v90, v57 offset:33104
	ds_write_b32 v90, v58 offset:33376
	ds_write_b32 v90, v59 offset:33648
	ds_write_b32 v90, v52 offset:32896
	ds_write_b32 v90, v53 offset:33168
	ds_write_b32 v90, v54 offset:33440
	ds_write_b32 v90, v55 offset:33712
	ds_write_b32 v90, v48 offset:32960
	ds_write_b32 v90, v49 offset:33232
	ds_write_b32 v90, v50 offset:33504
	ds_write_b32 v90, v51 offset:33776
	v_mad_u32_u24 v89, v95, s19, v97
	s_and_b32 s24, s24, 0x1fffff0
	ds_read_b128 v[50:53], v89 offset:32768
	s_sub_i32 s23, s23, s24
	s_lshl_b32 s23, s23, 7
	v_or3_b32 v48, s23, v74, v94
	v_or_b32_e32 v96, 4, v95
	v_add_u32_e32 v98, s25, v75
	v_ashrrev_i32_e32 v49, 31, v48
	v_lshlrev_b64 v[54:55], 12, v[92:93]
	v_or_b32_e32 v60, v96, v98
	v_lshlrev_b64 v[48:49], 1, v[48:49]
	v_lshl_add_u64 v[54:55], s[0:1], 0, v[54:55]
	v_ashrrev_i32_e32 v61, 31, v60
	v_lshl_add_u64 v[54:55], v[54:55], 0, v[48:49]
	s_waitcnt vmcnt(0)
	v_fmamk_f32 v56, v91, 0x3a800000, v88
	v_mul_f32_e32 v57, 0x4b800000, v56
	v_cmp_gt_f32_e32 vcc, s21, v56
	v_or_b32_e32 v91, v95, v98
	v_or_b32_e32 v62, 8, v91
	v_cndmask_b32_e32 v56, v56, v57, vcc
	v_rsq_f32_e32 v58, v56
	v_lshl_add_u64 v[56:57], v[60:61], 2, s[2:3]
	v_lshlrev_b64 v[60:61], 12, v[60:61]
	v_lshl_add_u64 v[60:61], s[0:1], 0, v[60:61]
	v_mul_f32_e32 v59, 0x45800000, v58
	v_cndmask_b32_e32 v58, v58, v59, vcc
	s_waitcnt lgkmcnt(0)
	v_pk_mul_f32 v[52:53], v[52:53], v[58:59] op_sel_hi:[1,0]
	v_pk_mul_f32 v[50:51], v[50:51], v[58:59] op_sel_hi:[1,0]
	v_ashrrev_i32_e32 v63, 31, v62
	v_cvt_pk_bf16_f32 v50, v50, v51
	v_cvt_pk_bf16_f32 v51, v52, v53
	global_store_dwordx2 v[54:55], v[50:51], off
	v_mov_b32_e32 v51, v151
	v_mad_u32_u24 v50, v96, s19, v97
	ds_read_b128 v[52:55], v50 offset:32768
	ds_read_b128 v[56:59], v50 offset:33856
	v_lshl_add_u64 v[60:61], v[60:61], 0, v[48:49]
	s_nop 0
	v_fmamk_f32 v51, v51, 0x3a800000, v88
	v_mul_f32_e32 v92, 0x4b800000, v51
	v_cmp_gt_f32_e32 vcc, s21, v51
	s_nop 1
	v_cndmask_b32_e32 v51, v51, v92, vcc
	v_rsq_f32_e32 v51, v51
	v_lshl_add_u64 v[92:93], v[62:63], 2, s[2:3]
	v_mul_f32_e32 v94, 0x45800000, v51
	v_cndmask_b32_e32 v94, v51, v94, vcc
	s_waitcnt lgkmcnt(1)
	v_pk_mul_f32 v[54:55], v[54:55], v[94:95] op_sel_hi:[1,0]
	v_pk_mul_f32 v[52:53], v[52:53], v[94:95] op_sel_hi:[1,0]
	s_nop 0
	v_cvt_pk_bf16_f32 v52, v52, v53
	v_cvt_pk_bf16_f32 v53, v54, v55
	global_store_dwordx2 v[60:61], v[52:53], off
	v_mov_b32_e32 v51, v152
	v_lshlrev_b64 v[52:53], 12, v[62:63]
	v_or_b32_e32 v60, 12, v91
	v_lshl_add_u64 v[52:53], s[0:1], 0, v[52:53]
	v_ashrrev_i32_e32 v61, 31, v60
	v_lshl_add_u64 v[52:53], v[52:53], 0, v[48:49]
	s_nop 0
	v_fmamk_f32 v51, v51, 0x3a800000, v88
	v_mul_f32_e32 v54, 0x4b800000, v51
	v_cmp_gt_f32_e32 vcc, s21, v51
	s_nop 1
	v_cndmask_b32_e32 v51, v51, v54, vcc
	v_rsq_f32_e32 v51, v51
	v_lshl_add_u64 v[54:55], v[60:61], 2, s[2:3]
	v_lshlrev_b64 v[60:61], 12, v[60:61]
	v_lshl_add_u64 v[60:61], s[0:1], 0, v[60:61]
	v_mul_f32_e32 v62, 0x45800000, v51
	v_cndmask_b32_e32 v62, v51, v62, vcc
	s_waitcnt lgkmcnt(0)
	v_pk_mul_f32 v[58:59], v[58:59], v[62:63] op_sel_hi:[1,0]
	v_pk_mul_f32 v[56:57], v[56:57], v[62:63] op_sel_hi:[1,0]
	v_lshl_add_u64 v[60:61], v[60:61], 0, v[48:49]
	v_cvt_pk_bf16_f32 v56, v56, v57
	v_cvt_pk_bf16_f32 v57, v58, v59
	global_store_dwordx2 v[52:53], v[56:57], off
	v_mov_b32_e32 v51, v153
	ds_read_b128 v[52:55], v50 offset:34944
	v_add_u32_e32 v56, v76, v64
	v_ashrrev_i32_e32 v57, 31, v56
	v_lshl_add_u64 v[58:59], v[56:57], 2, s[2:3]
	s_nop 0
	v_fmamk_f32 v51, v51, 0x3a800000, v88
	v_mul_f32_e32 v62, 0x4b800000, v51
	v_cmp_gt_f32_e32 vcc, s21, v51
	s_nop 1
	v_cndmask_b32_e32 v51, v51, v62, vcc
	v_rsq_f32_e32 v51, v51
	s_nop 0
	v_mul_f32_e32 v62, 0x45800000, v51
	v_cndmask_b32_e32 v62, v51, v62, vcc
	s_waitcnt lgkmcnt(0)
; __device__ __forceinline__ uint2 pack4v(f32x4 a) { uint2 r; r.x = pack2(a[0], a[1]); r.y = pack2(a[2], a[3]); return r; }
; template <typename PRE, typename OUT>
; __device__ __forceinline__ void gemm_epilogue(f32x4 (&acc)[4][4], u16* lds, PRE pre, OUT out) {
;     ...
;       for (int r = 0; r < 4; ++r) W[(fq * 4 + r) * EPS_STRIDE + j * 16 + fr] = pre(i, j, r, acc[i][j][r]);
; #pragma unroll
;     for (int q = 0; q < 4; ++q) {
;       const int row = q * 4 + (lane >> 4), c4 = lane & 15;
;       const f32x4 v = *(const f32x4*)(W + row * EPS_STRIDE + c4 * 4);
;       out(i * 16 + row, c4, v);
; __device__ void ph_gemm3(const P& p, u16* lds) {
;     ...
;     const int itn = it + gridDim.x; const bool more = itn < NTILES;
;     __syncthreads();
;     if (more) { g = ops(itn); gemm_prologue(g, lds); }
;     gemm_epilogue(acc, lds, [](int, int, int, float v) { return v; },
;       [&](int rowl, int c4, f32x4 v) {
;         const int m = mt * 128 + wm * 64 + rowl, n = nt * 128 + wn * 64 + c4 * 4;
;         const float rs = rsqrtf(p_ssq2[m] * (1.f / 1024.f) + EPS);
;         *(uint2*)(Qb + (size_t)m * 2048 + n) = pack4v(v * rs);
;       });
	v_pk_mul_f32 v[54:55], v[54:55], v[62:63] op_sel_hi:[1,0]
	v_pk_mul_f32 v[52:53], v[52:53], v[62:63] op_sel_hi:[1,0]
	s_nop 0
	v_cvt_pk_bf16_f32 v52, v52, v53
	v_cvt_pk_bf16_f32 v53, v54, v55
	global_store_dwordx2 v[60:61], v[52:53], off
	v_mov_b32_e32 v51, v154
	ds_write_b32 v90, v44 offset:32768
	ds_write_b32 v90, v45 offset:33040
	ds_write_b32 v90, v46 offset:33312
	ds_write_b32 v90, v47 offset:33584
	ds_write_b32 v90, v40 offset:32832
	ds_write_b32 v90, v41 offset:33104
	ds_write_b32 v90, v42 offset:33376
	ds_write_b32 v90, v43 offset:33648
	ds_write_b32 v90, v36 offset:32896
	ds_write_b32 v90, v37 offset:33168
	ds_write_b32 v90, v38 offset:33440
	ds_write_b32 v90, v39 offset:33712
	ds_write_b32 v90, v32 offset:32960
	ds_write_b32 v90, v33 offset:33232
	ds_write_b32 v90, v34 offset:33504
	ds_write_b32 v90, v35 offset:33776
	ds_read_b128 v[32:35], v89 offset:32768
	v_lshlrev_b64 v[36:37], 12, v[56:57]
	v_add_u32_e32 v52, v77, v64
	v_lshl_add_u64 v[36:37], s[0:1], 0, v[36:37]
	v_ashrrev_i32_e32 v53, 31, v52
	v_lshl_add_u64 v[36:37], v[36:37], 0, v[48:49]
	v_lshlrev_b64 v[42:43], 12, v[52:53]
	v_lshl_add_u64 v[42:43], s[0:1], 0, v[42:43]
	v_lshl_add_u64 v[42:43], v[42:43], 0, v[48:49]
	s_nop 0
	v_fmamk_f32 v38, v51, 0x3a800000, v88
	v_mul_f32_e32 v39, 0x4b800000, v38
	v_cmp_gt_f32_e32 vcc, s21, v38
	s_nop 1
	v_cndmask_b32_e32 v38, v38, v39, vcc
	v_rsq_f32_e32 v40, v38
	v_lshl_add_u64 v[38:39], v[52:53], 2, s[2:3]
	v_mul_f32_e32 v41, 0x45800000, v40
	v_cndmask_b32_e32 v40, v40, v41, vcc
	s_waitcnt lgkmcnt(0)
	v_pk_mul_f32 v[34:35], v[34:35], v[40:41] op_sel_hi:[1,0]
	v_pk_mul_f32 v[32:33], v[32:33], v[40:41] op_sel_hi:[1,0]
	v_add_u32_e32 v40, v78, v64
	v_cvt_pk_bf16_f32 v32, v32, v33
	v_cvt_pk_bf16_f32 v33, v34, v35
	global_store_dwordx2 v[36:37], v[32:33], off
	v_mov_b32_e32 v44, v155
	ds_read_b128 v[32:35], v50 offset:32768
	ds_read_b128 v[36:39], v50 offset:33856
	v_ashrrev_i32_e32 v41, 31, v40
	s_nop 0
	v_fmamk_f32 v44, v44, 0x3a800000, v88
	v_mul_f32_e32 v45, 0x4b800000, v44
	v_cmp_gt_f32_e32 vcc, s21, v44
	s_nop 1
	v_cndmask_b32_e32 v44, v44, v45, vcc
	v_rsq_f32_e32 v46, v44
	v_lshl_add_u64 v[44:45], v[40:41], 2, s[2:3]
	v_mul_f32_e32 v47, 0x45800000, v46
	v_cndmask_b32_e32 v46, v46, v47, vcc
	s_waitcnt lgkmcnt(1)
	v_pk_mul_f32 v[34:35], v[34:35], v[46:47] op_sel_hi:[1,0]
	v_pk_mul_f32 v[32:33], v[32:33], v[46:47] op_sel_hi:[1,0]
	s_nop 0
	v_cvt_pk_bf16_f32 v32, v32, v33
	v_cvt_pk_bf16_f32 v33, v34, v35
	global_store_dwordx2 v[42:43], v[32:33], off
	v_mov_b32_e32 v34, v156
	v_lshlrev_b64 v[32:33], 12, v[40:41]
	v_add_u32_e32 v42, v79, v64
	v_lshl_add_u64 v[32:33], s[0:1], 0, v[32:33]
	v_ashrrev_i32_e32 v43, 31, v42
	v_lshl_add_u64 v[32:33], v[32:33], 0, v[48:49]
	s_nop 0
	v_fmamk_f32 v34, v34, 0x3a800000, v88
	v_mul_f32_e32 v35, 0x4b800000, v34
	v_cmp_gt_f32_e32 vcc, s21, v34
	s_nop 1
	v_cndmask_b32_e32 v34, v34, v35, vcc
	v_rsq_f32_e32 v40, v34
	v_lshl_add_u64 v[34:35], v[42:43], 2, s[2:3]
	v_mul_f32_e32 v41, 0x45800000, v40
	v_cndmask_b32_e32 v40, v40, v41, vcc
	s_waitcnt lgkmcnt(0)
	v_pk_mul_f32 v[38:39], v[38:39], v[40:41] op_sel_hi:[1,0]
	v_pk_mul_f32 v[36:37], v[36:37], v[40:41] op_sel_hi:[1,0]
	s_nop 0
	v_cvt_pk_bf16_f32 v36, v36, v37
	v_cvt_pk_bf16_f32 v37, v38, v39
	global_store_dwordx2 v[32:33], v[36:37], off
	v_mov_b32_e32 v40, v157
	v_lshlrev_b64 v[38:39], 12, v[42:43]
	ds_read_b128 v[32:35], v50 offset:34944
	v_add_u32_e32 v36, v80, v64
	v_lshl_add_u64 v[38:39], s[0:1], 0, v[38:39]
	v_ashrrev_i32_e32 v37, 31, v36
	v_lshl_add_u64 v[38:39], v[38:39], 0, v[48:49]
	s_nop 0
	v_fmamk_f32 v40, v40, 0x3a800000, v88
	v_mul_f32_e32 v41, 0x4b800000, v40
	v_cmp_gt_f32_e32 vcc, s21, v40
	s_nop 1
	v_cndmask_b32_e32 v40, v40, v41, vcc
	v_rsq_f32_e32 v42, v40
	v_lshl_add_u64 v[40:41], v[36:37], 2, s[2:3]
	v_mul_f32_e32 v43, 0x45800000, v42
	v_cndmask_b32_e32 v42, v42, v43, vcc
	s_waitcnt lgkmcnt(0)
	v_pk_mul_f32 v[34:35], v[34:35], v[42:43] op_sel_hi:[1,0]
	v_pk_mul_f32 v[32:33], v[32:33], v[42:43] op_sel_hi:[1,0]
	s_nop 0
	v_cvt_pk_bf16_f32 v32, v32, v33
	v_cvt_pk_bf16_f32 v33, v34, v35
	global_store_dwordx2 v[38:39], v[32:33], off
	v_mov_b32_e32 v34, v158
	ds_write_b32 v90, v28 offset:32768
	ds_write_b32 v90, v29 offset:33040
	ds_write_b32 v90, v30 offset:33312
	ds_write_b32 v90, v31 offset:33584
	ds_write_b32 v90, v24 offset:32832
	ds_write_b32 v90, v25 offset:33104
	ds_write_b32 v90, v26 offset:33376
	ds_write_b32 v90, v27 offset:33648
	ds_write_b32 v90, v20 offset:32896
	ds_write_b32 v90, v21 offset:33168
	ds_write_b32 v90, v22 offset:33440
	ds_write_b32 v90, v23 offset:33712
	ds_write_b32 v90, v16 offset:32960
	ds_write_b32 v90, v17 offset:33232
	ds_write_b32 v90, v18 offset:33504
	ds_write_b32 v90, v19 offset:33776
	v_lshlrev_b64 v[20:21], 12, v[36:37]
	v_add_u32_e32 v32, v81, v64
	v_lshl_add_u64 v[20:21], s[0:1], 0, v[20:21]
	v_ashrrev_i32_e32 v33, 31, v32
	v_lshl_add_u64 v[20:21], v[20:21], 0, v[48:49]
	v_lshl_add_u64 v[22:23], v[32:33], 2, s[2:3]
	s_nop 0
	v_fmamk_f32 v16, v34, 0x3a800000, v88
	v_mul_f32_e32 v17, 0x4b800000, v16
	v_cmp_gt_f32_e32 vcc, s21, v16
	s_nop 1
	v_cndmask_b32_e32 v16, v16, v17, vcc
	v_rsq_f32_e32 v24, v16
	ds_read_b128 v[16:19], v89 offset:32768
	v_mul_f32_e32 v25, 0x45800000, v24
	v_cndmask_b32_e32 v24, v24, v25, vcc
	s_waitcnt lgkmcnt(0)
; __device__ __forceinline__ uint2 pack4v(f32x4 a) { uint2 r; r.x = pack2(a[0], a[1]); r.y = pack2(a[2], a[3]); return r; }
; template <typename PRE, typename OUT>
; __device__ __forceinline__ void gemm_epilogue(f32x4 (&acc)[4][4], u16* lds, PRE pre, OUT out) {
;     ...
;       for (int r = 0; r < 4; ++r) W[(fq * 4 + r) * EPS_STRIDE + j * 16 + fr] = pre(i, j, r, acc[i][j][r]);
; #pragma unroll
;     for (int q = 0; q < 4; ++q) {
;       const int row = q * 4 + (lane >> 4), c4 = lane & 15;
;       const f32x4 v = *(const f32x4*)(W + row * EPS_STRIDE + c4 * 4);
;       out(i * 16 + row, c4, v);
; __device__ void ph_gemm3(const P& p, u16* lds) {
;     ...
;     const int itn = it + gridDim.x; const bool more = itn < NTILES;
;     __syncthreads();
;     if (more) { g = ops(itn); gemm_prologue(g, lds); }
;     gemm_epilogue(acc, lds, [](int, int, int, float v) { return v; },
;       [&](int rowl, int c4, f32x4 v) {
;         const int m = mt * 128 + wm * 64 + rowl, n = nt * 128 + wn * 64 + c4 * 4;
;         const float rs = rsqrtf(p_ssq2[m] * (1.f / 1024.f) + EPS);
;         *(uint2*)(Qb + (size_t)m * 2048 + n) = pack4v(v * rs);
;       });
	v_pk_mul_f32 v[18:19], v[18:19], v[24:25] op_sel_hi:[1,0]
	v_pk_mul_f32 v[16:17], v[16:17], v[24:25] op_sel_hi:[1,0]
	v_add_u32_e32 v24, v82, v64
	v_cvt_pk_bf16_f32 v16, v16, v17
	v_cvt_pk_bf16_f32 v17, v18, v19
	global_store_dwordx2 v[20:21], v[16:17], off
	v_mov_b32_e32 v18, v159
	v_lshlrev_b64 v[16:17], 12, v[32:33]
	v_lshl_add_u64 v[28:29], s[0:1], 0, v[16:17]
	v_ashrrev_i32_e32 v25, 31, v24
	v_lshl_add_u64 v[28:29], v[28:29], 0, v[48:49]
	v_lshl_add_u64 v[26:27], v[24:25], 2, s[2:3]
	s_nop 0
	v_fmamk_f32 v16, v18, 0x3a800000, v88
	v_mul_f32_e32 v17, 0x4b800000, v16
	v_cmp_gt_f32_e32 vcc, s21, v16
	s_nop 1
	v_cndmask_b32_e32 v16, v16, v17, vcc
	v_rsq_f32_e32 v30, v16
	ds_read_b128 v[16:19], v50 offset:32768
	ds_read_b128 v[20:23], v50 offset:33856
	v_mul_f32_e32 v31, 0x45800000, v30
	v_cndmask_b32_e32 v30, v30, v31, vcc
	s_waitcnt lgkmcnt(1)
	v_pk_mul_f32 v[18:19], v[18:19], v[30:31] op_sel_hi:[1,0]
	v_pk_mul_f32 v[16:17], v[16:17], v[30:31] op_sel_hi:[1,0]
	s_nop 0
	v_cvt_pk_bf16_f32 v16, v16, v17
	v_cvt_pk_bf16_f32 v17, v18, v19
	global_store_dwordx2 v[28:29], v[16:17], off
	v_mov_b32_e32 v26, v160
	v_lshlrev_b64 v[18:19], 12, v[24:25]
	v_add_u32_e32 v16, v83, v64
	v_lshl_add_u64 v[18:19], s[0:1], 0, v[18:19]
	v_ashrrev_i32_e32 v17, 31, v16
	v_lshl_add_u64 v[18:19], v[18:19], 0, v[48:49]
	s_nop 0
	v_fmamk_f32 v24, v26, 0x3a800000, v88
	v_mul_f32_e32 v25, 0x4b800000, v24
	v_cmp_gt_f32_e32 vcc, s21, v24
	s_nop 1
	v_cndmask_b32_e32 v24, v24, v25, vcc
	v_rsq_f32_e32 v26, v24
	v_lshl_add_u64 v[24:25], v[16:17], 2, s[2:3]
	v_mul_f32_e32 v27, 0x45800000, v26
	v_cndmask_b32_e32 v26, v26, v27, vcc
	s_waitcnt lgkmcnt(0)
	v_pk_mul_f32 v[22:23], v[22:23], v[26:27] op_sel_hi:[1,0]
	v_pk_mul_f32 v[20:21], v[20:21], v[26:27] op_sel_hi:[1,0]
	s_nop 0
	v_cvt_pk_bf16_f32 v20, v20, v21
	v_cvt_pk_bf16_f32 v21, v22, v23
	global_store_dwordx2 v[18:19], v[20:21], off
	v_mov_b32_e32 v18, v161
	v_lshlrev_b64 v[22:23], 12, v[16:17]
	v_add_u32_e32 v20, v84, v64
	v_lshl_add_u64 v[22:23], s[0:1], 0, v[22:23]
	v_ashrrev_i32_e32 v21, 31, v20
	v_lshl_add_u64 v[22:23], v[22:23], 0, v[48:49]
	v_lshl_add_u64 v[24:25], v[20:21], 2, s[2:3]
	s_nop 0
	v_fmamk_f32 v16, v18, 0x3a800000, v88
	v_mul_f32_e32 v17, 0x4b800000, v16
	v_cmp_gt_f32_e32 vcc, s21, v16
	s_nop 1
	v_cndmask_b32_e32 v16, v16, v17, vcc
	v_rsq_f32_e32 v26, v16
	ds_read_b128 v[16:19], v50 offset:34944
	v_mul_f32_e32 v27, 0x45800000, v26
	v_cndmask_b32_e32 v26, v26, v27, vcc
	s_waitcnt lgkmcnt(0)
	v_pk_mul_f32 v[18:19], v[18:19], v[26:27] op_sel_hi:[1,0]
	v_pk_mul_f32 v[16:17], v[16:17], v[26:27] op_sel_hi:[1,0]
	s_nop 0
	v_cvt_pk_bf16_f32 v16, v16, v17
	v_cvt_pk_bf16_f32 v17, v18, v19
	global_store_dwordx2 v[22:23], v[16:17], off
	v_mov_b32_e32 v22, v162
	ds_write_b32 v90, v0 offset:32768
	ds_write_b32 v90, v1 offset:33040
	ds_write_b32 v90, v2 offset:33312
	ds_write_b32 v90, v3 offset:33584
	ds_write_b32 v90, v4 offset:32832
	ds_write_b32 v90, v5 offset:33104
	ds_write_b32 v90, v6 offset:33376
	ds_write_b32 v90, v7 offset:33648
	ds_write_b32 v90, v8 offset:32896
	ds_write_b32 v90, v9 offset:33168
	ds_write_b32 v90, v10 offset:33440
	ds_write_b32 v90, v11 offset:33712
	ds_write_b32 v90, v12 offset:32960
	ds_write_b32 v90, v13 offset:33232
	ds_write_b32 v90, v14 offset:33504
	ds_write_b32 v90, v15 offset:33776
	v_lshlrev_b64 v[18:19], 12, v[20:21]
	v_add_u32_e32 v16, v85, v64
	v_lshl_add_u64 v[4:5], s[0:1], 0, v[18:19]
	v_ashrrev_i32_e32 v17, 31, v16
	v_lshl_add_u64 v[4:5], v[4:5], 0, v[48:49]
	v_lshl_add_u64 v[20:21], v[16:17], 2, s[2:3]
	v_add_u32_e32 v8, v86, v64
	v_ashrrev_i32_e32 v9, 31, v8
	v_lshl_add_u64 v[10:11], v[8:9], 2, s[2:3]
	s_nop 0
	v_fmamk_f32 v0, v22, 0x3a800000, v88
	v_mul_f32_e32 v1, 0x4b800000, v0
	v_cmp_gt_f32_e32 vcc, s21, v0
	s_nop 1
	v_cndmask_b32_e32 v0, v0, v1, vcc
	v_rsq_f32_e32 v6, v0
	ds_read_b128 v[0:3], v89 offset:32768
	v_mul_f32_e32 v7, 0x45800000, v6
	v_cndmask_b32_e32 v6, v6, v7, vcc
	s_waitcnt lgkmcnt(0)
	v_pk_mul_f32 v[2:3], v[2:3], v[6:7] op_sel_hi:[1,0]
	v_pk_mul_f32 v[0:1], v[0:1], v[6:7] op_sel_hi:[1,0]
	s_nop 0
	v_cvt_pk_bf16_f32 v0, v0, v1
	v_cvt_pk_bf16_f32 v1, v2, v3
	global_store_dwordx2 v[4:5], v[0:1], off
	v_mov_b32_e32 v2, v163
	v_lshlrev_b64 v[0:1], 12, v[16:17]
	v_lshl_add_u64 v[4:5], s[0:1], 0, v[0:1]
	v_lshl_add_u64 v[12:13], v[4:5], 0, v[48:49]
	ds_read_b128 v[4:7], v50 offset:33856
	s_nop 0
	v_fmamk_f32 v0, v2, 0x3a800000, v88
	v_mul_f32_e32 v1, 0x4b800000, v0
	v_cmp_gt_f32_e32 vcc, s21, v0
	s_nop 1
	v_cndmask_b32_e32 v0, v0, v1, vcc
	v_rsq_f32_e32 v14, v0
	ds_read_b128 v[0:3], v50 offset:32768
	v_mul_f32_e32 v15, 0x45800000, v14
	v_cndmask_b32_e32 v14, v14, v15, vcc
	s_waitcnt lgkmcnt(0)
	v_pk_mul_f32 v[2:3], v[2:3], v[14:15] op_sel_hi:[1,0]
	v_pk_mul_f32 v[0:1], v[0:1], v[14:15] op_sel_hi:[1,0]
	s_nop 0
	v_cvt_pk_bf16_f32 v0, v0, v1
	v_cvt_pk_bf16_f32 v1, v2, v3
	global_store_dwordx2 v[12:13], v[0:1], off
	v_mov_b32_e32 v10, v164
	v_lshlrev_b64 v[2:3], 12, v[8:9]
	v_add_u32_e32 v0, v87, v64
	v_lshl_add_u64 v[2:3], s[0:1], 0, v[2:3]
	v_ashrrev_i32_e32 v1, 31, v0
	v_lshl_add_u64 v[2:3], v[2:3], 0, v[48:49]
	s_nop 0
	v_fmamk_f32 v8, v10, 0x3a800000, v88
	v_mul_f32_e32 v9, 0x4b800000, v8
	v_cmp_gt_f32_e32 vcc, s21, v8
	s_nop 1
	v_cndmask_b32_e32 v8, v8, v9, vcc
	v_rsq_f32_e32 v10, v8
	v_lshl_add_u64 v[8:9], v[0:1], 2, s[2:3]
	v_mul_f32_e32 v11, 0x45800000, v10
	v_cndmask_b32_e32 v10, v10, v11, vcc
	v_pk_mul_f32 v[6:7], v[6:7], v[10:11] op_sel_hi:[1,0]
	v_pk_mul_f32 v[4:5], v[4:5], v[10:11] op_sel_hi:[1,0]
	s_nop 0
	v_cvt_pk_bf16_f32 v4, v4, v5
	v_cvt_pk_bf16_f32 v5, v6, v7
	global_store_dwordx2 v[2:3], v[4:5], off
	v_mov_b32_e32 v2, v165
	v_lshlrev_b64 v[4:5], 12, v[0:1]
	v_lshl_add_u64 v[4:5], s[0:1], 0, v[4:5]
	v_lshl_add_u64 v[4:5], v[4:5], 0, v[48:49]
	s_nop 0
	v_fmamk_f32 v0, v2, 0x3a800000, v88
	v_mul_f32_e32 v1, 0x4b800000, v0
	v_cmp_gt_f32_e32 vcc, s21, v0
	s_nop 1
	v_cndmask_b32_e32 v0, v0, v1, vcc
	v_rsq_f32_e32 v6, v0
	ds_read_b128 v[0:3], v50 offset:34944
	v_mul_f32_e32 v7, 0x45800000, v6
	v_cndmask_b32_e32 v6, v6, v7, vcc
	s_waitcnt lgkmcnt(0)
	v_pk_mul_f32 v[2:3], v[2:3], v[6:7] op_sel_hi:[1,0]
	v_pk_mul_f32 v[0:1], v[0:1], v[6:7] op_sel_hi:[1,0]
	s_andn2_b64 vcc, exec, s[10:11]
	v_cvt_pk_bf16_f32 v0, v0, v1
	v_cvt_pk_bf16_f32 v1, v2, v3
	global_store_dwordx2 v[4:5], v[0:1], off
	s_cbranch_vccz .LBB0_699
